# nt on the bf16 residual-stream stores of the fused epilogues (XR / d_out bf16: consumed two phases later), XN stores unchanged
# speedup vs baseline: 1.0099x; 1.0083x over previous
.LBB0_650:
	s_or_b64 exec, exec, s[4:5]
	v_lshl_add_u64 v[130:131], v[148:149], 2, s[34:35]
	s_mov_b64 s[0:1], 0x102000
	v_add_co_u32_e32 v136, vcc, 0x102000, v130
	s_waitcnt lgkmcnt(1)
	v_lshl_add_u64 v[132:133], v[130:131], 0, s[0:1]
	s_mov_b64 s[0:1], 0x104000
	v_addc_co_u32_e32 v137, vcc, 0, v131, vcc
	v_lshl_add_u64 v[134:135], v[130:131], 0, s[0:1]
	v_add_co_u32_e32 v130, vcc, 0x104000, v130
	s_waitcnt lgkmcnt(0)
	s_barrier
	s_nop 0
	v_addc_co_u32_e32 v131, vcc, 0, v131, vcc
	global_load_dwordx4 v[146:149], v[134:135], off offset:64
	global_load_dwordx4 v[150:153], v[132:133], off offset:64
	global_load_dwordx4 v[138:141], v[132:133], off offset:512
	global_load_dwordx4 v[142:145], v[134:135], off offset:512
	global_load_dwordx4 v[154:157], v[136:137], off
	global_load_dwordx4 v[158:161], v[130:131], off
	s_nop 0
	global_load_dwordx4 v[130:133], v[132:133], off offset:576
	s_nop 0
	global_load_dwordx4 v[134:137], v[134:135], off offset:576
	v_or_b32_e32 v224, v185, v183
	s_waitcnt lgkmcnt(0)
	v_or_b32_e32 v225, v187, v224
	v_mov_b32_e32 v248, 0x7fc00000
	v_mov_b32_e32 v249, 0x7fc07fc0
	v_cmp_ne_u32_e32 vcc, 0, v224
	v_cmp_ne_u32_e64 s[0:1], 0, v225
	v_add_u32_e32 v246, v180, v162
	v_lshlrev_b32_e32 v246, 1, v246
	v_and_b32_e32 v247, 16, v0
	v_lshrrev_b32_e32 v247, 1, v247
	v_mad_u32_u24 v246, v247, 3, v246
	s_waitcnt vmcnt(0)
	ds_read_b64 v[244:245], v184 offset:8192
	s_waitcnt lgkmcnt(0)
	v_cndmask_b32_e32 v240, v118, v248, vcc
	v_cndmask_b32_e32 v241, v119, v248, vcc
	v_cndmask_b32_e32 v242, v120, v248, vcc
	v_cndmask_b32_e32 v243, v121, v248, vcc
	v_cvt_pk_bf16_f32 v216, v240, v241
	v_cvt_pk_bf16_f32 v217, v242, v243
	v_pk_mul_f32 v[118:119], v[118:119], v[244:245] op_sel:[0,1]
	v_pk_mul_f32 v[120:121], v[120:121], v[244:245] op_sel:[0,1]
	v_pk_fma_f32 v[118:119], v[154:155], v[118:119], v[158:159]
	v_pk_fma_f32 v[120:121], v[156:157], v[120:121], v[160:161]
	v_cvt_pk_bf16_f32 v232, v118, v119
	v_cvt_pk_bf16_f32 v233, v120, v121
	v_cndmask_b32_e64 v232, v232, v249, s[0:1]
	v_cndmask_b32_e64 v233, v233, v249, s[0:1]
	v_cndmask_b32_e32 v240, v122, v248, vcc
	v_cndmask_b32_e32 v241, v123, v248, vcc
	v_cndmask_b32_e32 v242, v124, v248, vcc
	v_cndmask_b32_e32 v243, v125, v248, vcc
	v_cvt_pk_bf16_f32 v218, v240, v241
	v_cvt_pk_bf16_f32 v219, v242, v243
	v_pk_mul_f32 v[122:123], v[122:123], v[244:245] op_sel:[0,1]
	v_pk_mul_f32 v[124:125], v[124:125], v[244:245] op_sel:[0,1]
	v_pk_fma_f32 v[122:123], v[150:151], v[122:123], v[146:147]
	v_pk_fma_f32 v[124:125], v[152:153], v[124:125], v[148:149]
	v_cvt_pk_bf16_f32 v234, v122, v123
	v_cvt_pk_bf16_f32 v235, v124, v125
	v_cndmask_b32_e64 v234, v234, v249, s[0:1]
	v_cndmask_b32_e64 v235, v235, v249, s[0:1]
	v_permlane16_swap_b32_e32 v216, v218
	v_permlane16_swap_b32_e32 v217, v219
	s_nop 1
	v_permlane16_swap_b32_e32 v232, v234
	v_permlane16_swap_b32_e32 v233, v235
	global_store_dwordx4 v246, v[216:219], s[56:57] sc1 nt
	global_store_dwordx4 v246, v[232:235], s[58:59] sc1
	v_cndmask_b32_e32 v240, v126, v248, vcc
	v_cndmask_b32_e32 v241, v127, v248, vcc
	v_cndmask_b32_e32 v242, v128, v248, vcc
	v_cndmask_b32_e32 v243, v129, v248, vcc
	v_cvt_pk_bf16_f32 v220, v240, v241
	v_cvt_pk_bf16_f32 v221, v242, v243
	v_pk_mul_f32 v[126:127], v[126:127], v[244:245] op_sel:[0,1]
	v_pk_mul_f32 v[128:129], v[128:129], v[244:245] op_sel:[0,1]
	v_pk_fma_f32 v[126:127], v[138:139], v[126:127], v[142:143]
	v_pk_fma_f32 v[128:129], v[140:141], v[128:129], v[144:145]
	v_cvt_pk_bf16_f32 v236, v126, v127
	v_cvt_pk_bf16_f32 v237, v128, v129
	v_cndmask_b32_e64 v236, v236, v249, s[0:1]
	v_cndmask_b32_e64 v237, v237, v249, s[0:1]
	v_cndmask_b32_e32 v240, v114, v248, vcc
	v_cndmask_b32_e32 v241, v115, v248, vcc
	v_cndmask_b32_e32 v242, v116, v248, vcc
	v_cndmask_b32_e32 v243, v117, v248, vcc
	v_cvt_pk_bf16_f32 v222, v240, v241
	v_cvt_pk_bf16_f32 v223, v242, v243
	v_pk_mul_f32 v[114:115], v[114:115], v[244:245] op_sel:[0,1]
	v_pk_mul_f32 v[116:117], v[116:117], v[244:245] op_sel:[0,1]
	v_pk_fma_f32 v[114:115], v[130:131], v[114:115], v[134:135]
	v_pk_fma_f32 v[116:117], v[132:133], v[116:117], v[136:137]
	v_cvt_pk_bf16_f32 v238, v114, v115
	v_cvt_pk_bf16_f32 v239, v116, v117
	v_cndmask_b32_e64 v238, v238, v249, s[0:1]
	v_cndmask_b32_e64 v239, v239, v249, s[0:1]
	v_permlane16_swap_b32_e32 v220, v222
	v_permlane16_swap_b32_e32 v221, v223
	s_nop 1
	v_permlane16_swap_b32_e32 v236, v238
	v_permlane16_swap_b32_e32 v237, v239
	global_store_dwordx4 v246, v[220:223], s[56:57] offset:256 sc1 nt
	global_store_dwordx4 v246, v[236:239], s[58:59] offset:256 sc1
	ds_read_b64 v[244:245], v184 offset:8320
	v_add_u32_e32 v247, 0x8000, v246
	s_waitcnt lgkmcnt(0)
	v_cndmask_b32_e32 v240, v110, v248, vcc
	v_cndmask_b32_e32 v241, v111, v248, vcc
	v_cndmask_b32_e32 v242, v112, v248, vcc
	v_cndmask_b32_e32 v243, v113, v248, vcc
	v_cvt_pk_bf16_f32 v216, v240, v241
	v_cvt_pk_bf16_f32 v217, v242, v243
	v_pk_mul_f32 v[110:111], v[110:111], v[244:245] op_sel:[0,1]
	v_pk_mul_f32 v[112:113], v[112:113], v[244:245] op_sel:[0,1]
	v_pk_fma_f32 v[110:111], v[154:155], v[110:111], v[158:159]
	v_pk_fma_f32 v[112:113], v[156:157], v[112:113], v[160:161]
	v_cvt_pk_bf16_f32 v232, v110, v111
	v_cvt_pk_bf16_f32 v233, v112, v113
	v_cndmask_b32_e64 v232, v232, v249, s[0:1]
	v_cndmask_b32_e64 v233, v233, v249, s[0:1]
	v_cndmask_b32_e32 v240, v106, v248, vcc
	v_cndmask_b32_e32 v241, v107, v248, vcc
	v_cndmask_b32_e32 v242, v108, v248, vcc
	v_cndmask_b32_e32 v243, v109, v248, vcc
	v_cvt_pk_bf16_f32 v218, v240, v241
	v_cvt_pk_bf16_f32 v219, v242, v243
	v_pk_mul_f32 v[106:107], v[106:107], v[244:245] op_sel:[0,1]
	v_pk_mul_f32 v[108:109], v[108:109], v[244:245] op_sel:[0,1]
	v_pk_fma_f32 v[106:107], v[150:151], v[106:107], v[146:147]
	v_pk_fma_f32 v[108:109], v[152:153], v[108:109], v[148:149]
	v_cvt_pk_bf16_f32 v234, v106, v107
	v_cvt_pk_bf16_f32 v235, v108, v109
	v_cndmask_b32_e64 v234, v234, v249, s[0:1]
	v_cndmask_b32_e64 v235, v235, v249, s[0:1]
	v_permlane16_swap_b32_e32 v216, v218
	v_permlane16_swap_b32_e32 v217, v219
	s_nop 1
	v_permlane16_swap_b32_e32 v232, v234
	v_permlane16_swap_b32_e32 v233, v235
	global_store_dwordx4 v247, v[216:219], s[56:57] sc1 nt
	global_store_dwordx4 v247, v[232:235], s[58:59] sc1
	v_cndmask_b32_e32 v240, v102, v248, vcc
	v_cndmask_b32_e32 v241, v103, v248, vcc
	v_cndmask_b32_e32 v242, v104, v248, vcc
	v_cndmask_b32_e32 v243, v105, v248, vcc
	v_cvt_pk_bf16_f32 v220, v240, v241
	v_cvt_pk_bf16_f32 v221, v242, v243
	v_pk_mul_f32 v[102:103], v[102:103], v[244:245] op_sel:[0,1]
	v_pk_mul_f32 v[104:105], v[104:105], v[244:245] op_sel:[0,1]
	v_pk_fma_f32 v[102:103], v[138:139], v[102:103], v[142:143]
	v_pk_fma_f32 v[104:105], v[140:141], v[104:105], v[144:145]
	v_cvt_pk_bf16_f32 v236, v102, v103
	v_cvt_pk_bf16_f32 v237, v104, v105
	v_cndmask_b32_e64 v236, v236, v249, s[0:1]
	v_cndmask_b32_e64 v237, v237, v249, s[0:1]
	v_cndmask_b32_e32 v240, v98, v248, vcc
	v_cndmask_b32_e32 v241, v99, v248, vcc
	v_cndmask_b32_e32 v242, v100, v248, vcc
	v_cndmask_b32_e32 v243, v101, v248, vcc
	v_cvt_pk_bf16_f32 v222, v240, v241
	v_cvt_pk_bf16_f32 v223, v242, v243
	v_pk_mul_f32 v[98:99], v[98:99], v[244:245] op_sel:[0,1]
	v_pk_mul_f32 v[100:101], v[100:101], v[244:245] op_sel:[0,1]
	v_pk_fma_f32 v[98:99], v[130:131], v[98:99], v[134:135]
	v_pk_fma_f32 v[100:101], v[132:133], v[100:101], v[136:137]
	v_cvt_pk_bf16_f32 v238, v98, v99
	v_cvt_pk_bf16_f32 v239, v100, v101
	v_cndmask_b32_e64 v238, v238, v249, s[0:1]
	v_cndmask_b32_e64 v239, v239, v249, s[0:1]
	v_permlane16_swap_b32_e32 v220, v222
	v_permlane16_swap_b32_e32 v221, v223
	s_nop 1
	v_permlane16_swap_b32_e32 v236, v238
	v_permlane16_swap_b32_e32 v237, v239
	global_store_dwordx4 v247, v[220:223], s[56:57] offset:256 sc1 nt
	global_store_dwordx4 v247, v[236:239], s[58:59] offset:256 sc1
	ds_read_b64 v[244:245], v184 offset:8448
	v_add_u32_e32 v247, 0x10000, v246
	s_waitcnt lgkmcnt(0)
	v_cndmask_b32_e32 v240, v94, v248, vcc
	v_cndmask_b32_e32 v241, v95, v248, vcc
	v_cndmask_b32_e32 v242, v96, v248, vcc
	v_cndmask_b32_e32 v243, v97, v248, vcc
	v_cvt_pk_bf16_f32 v216, v240, v241
	v_cvt_pk_bf16_f32 v217, v242, v243
	v_pk_mul_f32 v[94:95], v[94:95], v[244:245] op_sel:[0,1]
	v_pk_mul_f32 v[96:97], v[96:97], v[244:245] op_sel:[0,1]
	v_pk_fma_f32 v[94:95], v[154:155], v[94:95], v[158:159]
	v_pk_fma_f32 v[96:97], v[156:157], v[96:97], v[160:161]
	v_cvt_pk_bf16_f32 v232, v94, v95
	v_cvt_pk_bf16_f32 v233, v96, v97
	v_cndmask_b32_e64 v232, v232, v249, s[0:1]
	v_cndmask_b32_e64 v233, v233, v249, s[0:1]
	v_cndmask_b32_e32 v240, v90, v248, vcc
	v_cndmask_b32_e32 v241, v91, v248, vcc
	v_cndmask_b32_e32 v242, v92, v248, vcc
	v_cndmask_b32_e32 v243, v93, v248, vcc
	v_cvt_pk_bf16_f32 v218, v240, v241
	v_cvt_pk_bf16_f32 v219, v242, v243
	v_pk_mul_f32 v[90:91], v[90:91], v[244:245] op_sel:[0,1]
	v_pk_mul_f32 v[92:93], v[92:93], v[244:245] op_sel:[0,1]
	v_pk_fma_f32 v[90:91], v[150:151], v[90:91], v[146:147]
	v_pk_fma_f32 v[92:93], v[152:153], v[92:93], v[148:149]
	v_cvt_pk_bf16_f32 v234, v90, v91
	v_cvt_pk_bf16_f32 v235, v92, v93
	v_cndmask_b32_e64 v234, v234, v249, s[0:1]
	v_cndmask_b32_e64 v235, v235, v249, s[0:1]
	v_permlane16_swap_b32_e32 v216, v218
	v_permlane16_swap_b32_e32 v217, v219
	s_nop 1
	v_permlane16_swap_b32_e32 v232, v234
	v_permlane16_swap_b32_e32 v233, v235
	global_store_dwordx4 v247, v[216:219], s[56:57] sc1 nt
	global_store_dwordx4 v247, v[232:235], s[58:59] sc1
	v_cndmask_b32_e32 v240, v86, v248, vcc
	v_cndmask_b32_e32 v241, v87, v248, vcc
	v_cndmask_b32_e32 v242, v88, v248, vcc
	v_cndmask_b32_e32 v243, v89, v248, vcc
	v_cvt_pk_bf16_f32 v220, v240, v241
	v_cvt_pk_bf16_f32 v221, v242, v243
	v_pk_mul_f32 v[86:87], v[86:87], v[244:245] op_sel:[0,1]
	v_pk_mul_f32 v[88:89], v[88:89], v[244:245] op_sel:[0,1]
	v_pk_fma_f32 v[86:87], v[138:139], v[86:87], v[142:143]
	v_pk_fma_f32 v[88:89], v[140:141], v[88:89], v[144:145]
	v_cvt_pk_bf16_f32 v236, v86, v87
	v_cvt_pk_bf16_f32 v237, v88, v89
	v_cndmask_b32_e64 v236, v236, v249, s[0:1]
	v_cndmask_b32_e64 v237, v237, v249, s[0:1]
	v_cndmask_b32_e32 v240, v82, v248, vcc
	v_cndmask_b32_e32 v241, v83, v248, vcc
	v_cndmask_b32_e32 v242, v84, v248, vcc
	v_cndmask_b32_e32 v243, v85, v248, vcc
	v_cvt_pk_bf16_f32 v222, v240, v241
	v_cvt_pk_bf16_f32 v223, v242, v243
	v_pk_mul_f32 v[82:83], v[82:83], v[244:245] op_sel:[0,1]
	v_pk_mul_f32 v[84:85], v[84:85], v[244:245] op_sel:[0,1]
	v_pk_fma_f32 v[82:83], v[130:131], v[82:83], v[134:135]
	v_pk_fma_f32 v[84:85], v[132:133], v[84:85], v[136:137]
	v_cvt_pk_bf16_f32 v238, v82, v83
	v_cvt_pk_bf16_f32 v239, v84, v85
	v_cndmask_b32_e64 v238, v238, v249, s[0:1]
	v_cndmask_b32_e64 v239, v239, v249, s[0:1]
	v_permlane16_swap_b32_e32 v220, v222
	v_permlane16_swap_b32_e32 v221, v223
	s_nop 1
	v_permlane16_swap_b32_e32 v236, v238
	v_permlane16_swap_b32_e32 v237, v239
	global_store_dwordx4 v247, v[220:223], s[56:57] offset:256 sc1 nt
	global_store_dwordx4 v247, v[236:239], s[58:59] offset:256 sc1
	ds_read_b64 v[244:245], v184 offset:8576
	v_add_u32_e32 v247, 0x18000, v246
	s_waitcnt lgkmcnt(0)
	v_cndmask_b32_e32 v240, v78, v248, vcc
	v_cndmask_b32_e32 v241, v79, v248, vcc
	v_cndmask_b32_e32 v242, v80, v248, vcc
	v_cndmask_b32_e32 v243, v81, v248, vcc
	v_cvt_pk_bf16_f32 v216, v240, v241
	v_cvt_pk_bf16_f32 v217, v242, v243
	v_pk_mul_f32 v[78:79], v[78:79], v[244:245] op_sel:[0,1]
	v_pk_mul_f32 v[80:81], v[80:81], v[244:245] op_sel:[0,1]
	v_pk_fma_f32 v[78:79], v[154:155], v[78:79], v[158:159]
	v_pk_fma_f32 v[80:81], v[156:157], v[80:81], v[160:161]
	v_cvt_pk_bf16_f32 v232, v78, v79
	v_cvt_pk_bf16_f32 v233, v80, v81
	v_cndmask_b32_e64 v232, v232, v249, s[0:1]
	v_cndmask_b32_e64 v233, v233, v249, s[0:1]
	v_cndmask_b32_e32 v240, v74, v248, vcc
	v_cndmask_b32_e32 v241, v75, v248, vcc
	v_cndmask_b32_e32 v242, v76, v248, vcc
	v_cndmask_b32_e32 v243, v77, v248, vcc
	v_cvt_pk_bf16_f32 v218, v240, v241
	v_cvt_pk_bf16_f32 v219, v242, v243
	v_pk_mul_f32 v[74:75], v[74:75], v[244:245] op_sel:[0,1]
	v_pk_mul_f32 v[76:77], v[76:77], v[244:245] op_sel:[0,1]
	v_pk_fma_f32 v[74:75], v[150:151], v[74:75], v[146:147]
	v_pk_fma_f32 v[76:77], v[152:153], v[76:77], v[148:149]
	v_cvt_pk_bf16_f32 v234, v74, v75
	v_cvt_pk_bf16_f32 v235, v76, v77
	v_cndmask_b32_e64 v234, v234, v249, s[0:1]
	v_cndmask_b32_e64 v235, v235, v249, s[0:1]
	v_permlane16_swap_b32_e32 v216, v218
	v_permlane16_swap_b32_e32 v217, v219
	s_nop 1
	v_permlane16_swap_b32_e32 v232, v234
	v_permlane16_swap_b32_e32 v233, v235
	global_store_dwordx4 v247, v[216:219], s[56:57] sc1 nt
	global_store_dwordx4 v247, v[232:235], s[58:59] sc1
	v_cndmask_b32_e32 v240, v70, v248, vcc
	v_cndmask_b32_e32 v241, v71, v248, vcc
	v_cndmask_b32_e32 v242, v72, v248, vcc
	v_cndmask_b32_e32 v243, v73, v248, vcc
	v_cvt_pk_bf16_f32 v220, v240, v241
	v_cvt_pk_bf16_f32 v221, v242, v243
	v_pk_mul_f32 v[70:71], v[70:71], v[244:245] op_sel:[0,1]
	v_pk_mul_f32 v[72:73], v[72:73], v[244:245] op_sel:[0,1]
	v_pk_fma_f32 v[70:71], v[138:139], v[70:71], v[142:143]
	v_pk_fma_f32 v[72:73], v[140:141], v[72:73], v[144:145]
	v_cvt_pk_bf16_f32 v236, v70, v71
	v_cvt_pk_bf16_f32 v237, v72, v73
	v_cndmask_b32_e64 v236, v236, v249, s[0:1]
	v_cndmask_b32_e64 v237, v237, v249, s[0:1]
	v_cndmask_b32_e32 v240, v66, v248, vcc
	v_cndmask_b32_e32 v241, v67, v248, vcc
	v_cndmask_b32_e32 v242, v68, v248, vcc
	v_cndmask_b32_e32 v243, v69, v248, vcc
	v_cvt_pk_bf16_f32 v222, v240, v241
	v_cvt_pk_bf16_f32 v223, v242, v243
	v_pk_mul_f32 v[66:67], v[66:67], v[244:245] op_sel:[0,1]
	v_pk_mul_f32 v[68:69], v[68:69], v[244:245] op_sel:[0,1]
	v_pk_fma_f32 v[66:67], v[130:131], v[66:67], v[134:135]
	v_pk_fma_f32 v[68:69], v[132:133], v[68:69], v[136:137]
	v_cvt_pk_bf16_f32 v238, v66, v67
	v_cvt_pk_bf16_f32 v239, v68, v69
	v_cndmask_b32_e64 v238, v238, v249, s[0:1]
	v_cndmask_b32_e64 v239, v239, v249, s[0:1]
	v_permlane16_swap_b32_e32 v220, v222
	v_permlane16_swap_b32_e32 v221, v223
	s_nop 1
	v_permlane16_swap_b32_e32 v236, v238
	v_permlane16_swap_b32_e32 v237, v239
	global_store_dwordx4 v247, v[220:223], s[56:57] offset:256 sc1 nt
	global_store_dwordx4 v247, v[236:239], s[58:59] offset:256 sc1
	ds_read_b64 v[244:245], v184 offset:9216
	v_add_u32_e32 v247, 0x40000, v246
	s_waitcnt lgkmcnt(0)
	v_cndmask_b32_e32 v240, v62, v248, vcc
	v_cndmask_b32_e32 v241, v63, v248, vcc
	v_cndmask_b32_e32 v242, v64, v248, vcc
	v_cndmask_b32_e32 v243, v65, v248, vcc
	v_cvt_pk_bf16_f32 v216, v240, v241
	v_cvt_pk_bf16_f32 v217, v242, v243
	v_pk_mul_f32 v[62:63], v[62:63], v[244:245] op_sel:[0,1]
	v_pk_mul_f32 v[64:65], v[64:65], v[244:245] op_sel:[0,1]
	v_pk_fma_f32 v[62:63], v[154:155], v[62:63], v[158:159]
	v_pk_fma_f32 v[64:65], v[156:157], v[64:65], v[160:161]
	v_cvt_pk_bf16_f32 v232, v62, v63
	v_cvt_pk_bf16_f32 v233, v64, v65
	v_cndmask_b32_e64 v232, v232, v249, s[0:1]
	v_cndmask_b32_e64 v233, v233, v249, s[0:1]
	v_cndmask_b32_e32 v240, v58, v248, vcc
	v_cndmask_b32_e32 v241, v59, v248, vcc
	v_cndmask_b32_e32 v242, v60, v248, vcc
	v_cndmask_b32_e32 v243, v61, v248, vcc
	v_cvt_pk_bf16_f32 v218, v240, v241
	v_cvt_pk_bf16_f32 v219, v242, v243
	v_pk_mul_f32 v[58:59], v[58:59], v[244:245] op_sel:[0,1]
	v_pk_mul_f32 v[60:61], v[60:61], v[244:245] op_sel:[0,1]
	v_pk_fma_f32 v[58:59], v[150:151], v[58:59], v[146:147]
	v_pk_fma_f32 v[60:61], v[152:153], v[60:61], v[148:149]
	v_cvt_pk_bf16_f32 v234, v58, v59
	v_cvt_pk_bf16_f32 v235, v60, v61
	v_cndmask_b32_e64 v234, v234, v249, s[0:1]
	v_cndmask_b32_e64 v235, v235, v249, s[0:1]
	v_permlane16_swap_b32_e32 v216, v218
	v_permlane16_swap_b32_e32 v217, v219
	s_nop 1
	v_permlane16_swap_b32_e32 v232, v234
	v_permlane16_swap_b32_e32 v233, v235
	global_store_dwordx4 v247, v[216:219], s[56:57] sc1 nt
	global_store_dwordx4 v247, v[232:235], s[58:59] sc1
	v_cndmask_b32_e32 v240, v54, v248, vcc
	v_cndmask_b32_e32 v241, v55, v248, vcc
	v_cndmask_b32_e32 v242, v56, v248, vcc
	v_cndmask_b32_e32 v243, v57, v248, vcc
	v_cvt_pk_bf16_f32 v220, v240, v241
	v_cvt_pk_bf16_f32 v221, v242, v243
	v_pk_mul_f32 v[54:55], v[54:55], v[244:245] op_sel:[0,1]
	v_pk_mul_f32 v[56:57], v[56:57], v[244:245] op_sel:[0,1]
	v_pk_fma_f32 v[54:55], v[138:139], v[54:55], v[142:143]
	v_pk_fma_f32 v[56:57], v[140:141], v[56:57], v[144:145]
	v_cvt_pk_bf16_f32 v236, v54, v55
	v_cvt_pk_bf16_f32 v237, v56, v57
	v_cndmask_b32_e64 v236, v236, v249, s[0:1]
	v_cndmask_b32_e64 v237, v237, v249, s[0:1]
	v_cndmask_b32_e32 v240, v50, v248, vcc
	v_cndmask_b32_e32 v241, v51, v248, vcc
	v_cndmask_b32_e32 v242, v52, v248, vcc
	v_cndmask_b32_e32 v243, v53, v248, vcc
	v_cvt_pk_bf16_f32 v222, v240, v241
	v_cvt_pk_bf16_f32 v223, v242, v243
	v_pk_mul_f32 v[50:51], v[50:51], v[244:245] op_sel:[0,1]
	v_pk_mul_f32 v[52:53], v[52:53], v[244:245] op_sel:[0,1]
	v_pk_fma_f32 v[50:51], v[130:131], v[50:51], v[134:135]
	v_pk_fma_f32 v[52:53], v[132:133], v[52:53], v[136:137]
	v_cvt_pk_bf16_f32 v238, v50, v51
	v_cvt_pk_bf16_f32 v239, v52, v53
	v_cndmask_b32_e64 v238, v238, v249, s[0:1]
	v_cndmask_b32_e64 v239, v239, v249, s[0:1]
	v_permlane16_swap_b32_e32 v220, v222
	v_permlane16_swap_b32_e32 v221, v223
	s_nop 1
	v_permlane16_swap_b32_e32 v236, v238
	v_permlane16_swap_b32_e32 v237, v239
	global_store_dwordx4 v247, v[220:223], s[56:57] offset:256 sc1 nt
	global_store_dwordx4 v247, v[236:239], s[58:59] offset:256 sc1
	ds_read_b64 v[244:245], v184 offset:9344
	v_add_u32_e32 v247, 0x48000, v246
	s_waitcnt lgkmcnt(0)
	v_cndmask_b32_e32 v240, v46, v248, vcc
	v_cndmask_b32_e32 v241, v47, v248, vcc
	v_cndmask_b32_e32 v242, v48, v248, vcc
	v_cndmask_b32_e32 v243, v49, v248, vcc
	v_cvt_pk_bf16_f32 v216, v240, v241
	v_cvt_pk_bf16_f32 v217, v242, v243
	v_pk_mul_f32 v[46:47], v[46:47], v[244:245] op_sel:[0,1]
	v_pk_mul_f32 v[48:49], v[48:49], v[244:245] op_sel:[0,1]
	v_pk_fma_f32 v[46:47], v[154:155], v[46:47], v[158:159]
	v_pk_fma_f32 v[48:49], v[156:157], v[48:49], v[160:161]
	v_cvt_pk_bf16_f32 v232, v46, v47
	v_cvt_pk_bf16_f32 v233, v48, v49
	v_cndmask_b32_e64 v232, v232, v249, s[0:1]
	v_cndmask_b32_e64 v233, v233, v249, s[0:1]
	v_cndmask_b32_e32 v240, v42, v248, vcc
	v_cndmask_b32_e32 v241, v43, v248, vcc
	v_cndmask_b32_e32 v242, v44, v248, vcc
	v_cndmask_b32_e32 v243, v45, v248, vcc
	v_cvt_pk_bf16_f32 v218, v240, v241
	v_cvt_pk_bf16_f32 v219, v242, v243
	v_pk_mul_f32 v[42:43], v[42:43], v[244:245] op_sel:[0,1]
	v_pk_mul_f32 v[44:45], v[44:45], v[244:245] op_sel:[0,1]
	v_pk_fma_f32 v[42:43], v[150:151], v[42:43], v[146:147]
	v_pk_fma_f32 v[44:45], v[152:153], v[44:45], v[148:149]
	v_cvt_pk_bf16_f32 v234, v42, v43
	v_cvt_pk_bf16_f32 v235, v44, v45
	v_cndmask_b32_e64 v234, v234, v249, s[0:1]
	v_cndmask_b32_e64 v235, v235, v249, s[0:1]
	v_permlane16_swap_b32_e32 v216, v218
	v_permlane16_swap_b32_e32 v217, v219
	s_nop 1
	v_permlane16_swap_b32_e32 v232, v234
	v_permlane16_swap_b32_e32 v233, v235
	global_store_dwordx4 v247, v[216:219], s[56:57] sc1 nt
	global_store_dwordx4 v247, v[232:235], s[58:59] sc1
	v_cndmask_b32_e32 v240, v38, v248, vcc
	v_cndmask_b32_e32 v241, v39, v248, vcc
	v_cndmask_b32_e32 v242, v40, v248, vcc
	v_cndmask_b32_e32 v243, v41, v248, vcc
	v_cvt_pk_bf16_f32 v220, v240, v241
	v_cvt_pk_bf16_f32 v221, v242, v243
	v_pk_mul_f32 v[38:39], v[38:39], v[244:245] op_sel:[0,1]
	v_pk_mul_f32 v[40:41], v[40:41], v[244:245] op_sel:[0,1]
	v_pk_fma_f32 v[38:39], v[138:139], v[38:39], v[142:143]
	v_pk_fma_f32 v[40:41], v[140:141], v[40:41], v[144:145]
	v_cvt_pk_bf16_f32 v236, v38, v39
	v_cvt_pk_bf16_f32 v237, v40, v41
	v_cndmask_b32_e64 v236, v236, v249, s[0:1]
	v_cndmask_b32_e64 v237, v237, v249, s[0:1]
	v_cndmask_b32_e32 v240, v34, v248, vcc
	v_cndmask_b32_e32 v241, v35, v248, vcc
	v_cndmask_b32_e32 v242, v36, v248, vcc
	v_cndmask_b32_e32 v243, v37, v248, vcc
	v_cvt_pk_bf16_f32 v222, v240, v241
	v_cvt_pk_bf16_f32 v223, v242, v243
	v_pk_mul_f32 v[34:35], v[34:35], v[244:245] op_sel:[0,1]
	v_pk_mul_f32 v[36:37], v[36:37], v[244:245] op_sel:[0,1]
	v_pk_fma_f32 v[34:35], v[130:131], v[34:35], v[134:135]
	v_pk_fma_f32 v[36:37], v[132:133], v[36:37], v[136:137]
	v_cvt_pk_bf16_f32 v238, v34, v35
	v_cvt_pk_bf16_f32 v239, v36, v37
	v_cndmask_b32_e64 v238, v238, v249, s[0:1]
	v_cndmask_b32_e64 v239, v239, v249, s[0:1]
	v_permlane16_swap_b32_e32 v220, v222
	v_permlane16_swap_b32_e32 v221, v223
	s_nop 1
	v_permlane16_swap_b32_e32 v236, v238
	v_permlane16_swap_b32_e32 v237, v239
	global_store_dwordx4 v247, v[220:223], s[56:57] offset:256 sc1 nt
	global_store_dwordx4 v247, v[236:239], s[58:59] offset:256 sc1
	ds_read_b64 v[244:245], v184 offset:9472
	v_add_u32_e32 v247, 0x50000, v246
	s_waitcnt lgkmcnt(0)
	v_cndmask_b32_e32 v240, v30, v248, vcc
	v_cndmask_b32_e32 v241, v31, v248, vcc
	v_cndmask_b32_e32 v242, v32, v248, vcc
	v_cndmask_b32_e32 v243, v33, v248, vcc
	v_cvt_pk_bf16_f32 v216, v240, v241
	v_cvt_pk_bf16_f32 v217, v242, v243
	v_pk_mul_f32 v[30:31], v[30:31], v[244:245] op_sel:[0,1]
	v_pk_mul_f32 v[32:33], v[32:33], v[244:245] op_sel:[0,1]
	v_pk_fma_f32 v[30:31], v[154:155], v[30:31], v[158:159]
	v_pk_fma_f32 v[32:33], v[156:157], v[32:33], v[160:161]
	v_cvt_pk_bf16_f32 v232, v30, v31
	v_cvt_pk_bf16_f32 v233, v32, v33
	v_cndmask_b32_e64 v232, v232, v249, s[0:1]
	v_cndmask_b32_e64 v233, v233, v249, s[0:1]
	v_cndmask_b32_e32 v240, v26, v248, vcc
	v_cndmask_b32_e32 v241, v27, v248, vcc
	v_cndmask_b32_e32 v242, v28, v248, vcc
	v_cndmask_b32_e32 v243, v29, v248, vcc
	v_cvt_pk_bf16_f32 v218, v240, v241
	v_cvt_pk_bf16_f32 v219, v242, v243
	v_pk_mul_f32 v[26:27], v[26:27], v[244:245] op_sel:[0,1]
	v_pk_mul_f32 v[28:29], v[28:29], v[244:245] op_sel:[0,1]
	v_pk_fma_f32 v[26:27], v[150:151], v[26:27], v[146:147]
	v_pk_fma_f32 v[28:29], v[152:153], v[28:29], v[148:149]
	v_cvt_pk_bf16_f32 v234, v26, v27
	v_cvt_pk_bf16_f32 v235, v28, v29
	v_cndmask_b32_e64 v234, v234, v249, s[0:1]
	v_cndmask_b32_e64 v235, v235, v249, s[0:1]
	v_permlane16_swap_b32_e32 v216, v218
	v_permlane16_swap_b32_e32 v217, v219
	s_nop 1
	v_permlane16_swap_b32_e32 v232, v234
	v_permlane16_swap_b32_e32 v233, v235
	global_store_dwordx4 v247, v[216:219], s[56:57] sc1 nt
	global_store_dwordx4 v247, v[232:235], s[58:59] sc1
	v_cndmask_b32_e32 v240, v22, v248, vcc
	v_cndmask_b32_e32 v241, v23, v248, vcc
	v_cndmask_b32_e32 v242, v24, v248, vcc
	v_cndmask_b32_e32 v243, v25, v248, vcc
	v_cvt_pk_bf16_f32 v220, v240, v241
	v_cvt_pk_bf16_f32 v221, v242, v243
	v_pk_mul_f32 v[22:23], v[22:23], v[244:245] op_sel:[0,1]
	v_pk_mul_f32 v[24:25], v[24:25], v[244:245] op_sel:[0,1]
	v_pk_fma_f32 v[22:23], v[138:139], v[22:23], v[142:143]
	v_pk_fma_f32 v[24:25], v[140:141], v[24:25], v[144:145]
	v_cvt_pk_bf16_f32 v236, v22, v23
	v_cvt_pk_bf16_f32 v237, v24, v25
	v_cndmask_b32_e64 v236, v236, v249, s[0:1]
	v_cndmask_b32_e64 v237, v237, v249, s[0:1]
	v_cndmask_b32_e32 v240, v18, v248, vcc
	v_cndmask_b32_e32 v241, v19, v248, vcc
	v_cndmask_b32_e32 v242, v20, v248, vcc
	v_cndmask_b32_e32 v243, v21, v248, vcc
	v_cvt_pk_bf16_f32 v222, v240, v241
	v_cvt_pk_bf16_f32 v223, v242, v243
	v_pk_mul_f32 v[18:19], v[18:19], v[244:245] op_sel:[0,1]
	v_pk_mul_f32 v[20:21], v[20:21], v[244:245] op_sel:[0,1]
	v_pk_fma_f32 v[18:19], v[130:131], v[18:19], v[134:135]
	v_pk_fma_f32 v[20:21], v[132:133], v[20:21], v[136:137]
	v_cvt_pk_bf16_f32 v238, v18, v19
	v_cvt_pk_bf16_f32 v239, v20, v21
	v_cndmask_b32_e64 v238, v238, v249, s[0:1]
	v_cndmask_b32_e64 v239, v239, v249, s[0:1]
	v_permlane16_swap_b32_e32 v220, v222
	v_permlane16_swap_b32_e32 v221, v223
	s_nop 1
	v_permlane16_swap_b32_e32 v236, v238
	v_permlane16_swap_b32_e32 v237, v239
	global_store_dwordx4 v247, v[220:223], s[56:57] offset:256 sc1 nt
	global_store_dwordx4 v247, v[236:239], s[58:59] offset:256 sc1
	ds_read_b64 v[244:245], v184 offset:9600
	v_add_u32_e32 v247, 0x58000, v246
	s_waitcnt lgkmcnt(0)
	v_cndmask_b32_e32 v240, v14, v248, vcc
	v_cndmask_b32_e32 v241, v15, v248, vcc
	v_cndmask_b32_e32 v242, v16, v248, vcc
	v_cndmask_b32_e32 v243, v17, v248, vcc
	v_cvt_pk_bf16_f32 v216, v240, v241
	v_cvt_pk_bf16_f32 v217, v242, v243
	v_pk_mul_f32 v[14:15], v[14:15], v[244:245] op_sel:[0,1]
	v_pk_mul_f32 v[16:17], v[16:17], v[244:245] op_sel:[0,1]
	v_pk_fma_f32 v[14:15], v[154:155], v[14:15], v[158:159]
	v_pk_fma_f32 v[16:17], v[156:157], v[16:17], v[160:161]
	v_cvt_pk_bf16_f32 v232, v14, v15
	v_cvt_pk_bf16_f32 v233, v16, v17
	v_cndmask_b32_e64 v232, v232, v249, s[0:1]
	v_cndmask_b32_e64 v233, v233, v249, s[0:1]
	v_cndmask_b32_e32 v240, v10, v248, vcc
	v_cndmask_b32_e32 v241, v11, v248, vcc
	v_cndmask_b32_e32 v242, v12, v248, vcc
	v_cndmask_b32_e32 v243, v13, v248, vcc
	v_cvt_pk_bf16_f32 v218, v240, v241
	v_cvt_pk_bf16_f32 v219, v242, v243
	v_pk_mul_f32 v[10:11], v[10:11], v[244:245] op_sel:[0,1]
	v_pk_mul_f32 v[12:13], v[12:13], v[244:245] op_sel:[0,1]
	v_pk_fma_f32 v[10:11], v[150:151], v[10:11], v[146:147]
	v_pk_fma_f32 v[12:13], v[152:153], v[12:13], v[148:149]
	v_cvt_pk_bf16_f32 v234, v10, v11
	v_cvt_pk_bf16_f32 v235, v12, v13
	v_cndmask_b32_e64 v234, v234, v249, s[0:1]
	v_cndmask_b32_e64 v235, v235, v249, s[0:1]
	v_permlane16_swap_b32_e32 v216, v218
	v_permlane16_swap_b32_e32 v217, v219
	s_nop 1
	v_permlane16_swap_b32_e32 v232, v234
	v_permlane16_swap_b32_e32 v233, v235
	global_store_dwordx4 v247, v[216:219], s[56:57] sc1 nt
	global_store_dwordx4 v247, v[232:235], s[58:59] sc1
	v_cndmask_b32_e32 v240, v6, v248, vcc
	v_cndmask_b32_e32 v241, v7, v248, vcc
	v_cndmask_b32_e32 v242, v8, v248, vcc
	v_cndmask_b32_e32 v243, v9, v248, vcc
	v_cvt_pk_bf16_f32 v220, v240, v241
	v_cvt_pk_bf16_f32 v221, v242, v243
	v_pk_mul_f32 v[6:7], v[6:7], v[244:245] op_sel:[0,1]
	v_pk_mul_f32 v[8:9], v[8:9], v[244:245] op_sel:[0,1]
	v_pk_fma_f32 v[6:7], v[138:139], v[6:7], v[142:143]
	v_pk_fma_f32 v[8:9], v[140:141], v[8:9], v[144:145]
	v_cvt_pk_bf16_f32 v236, v6, v7
	v_cvt_pk_bf16_f32 v237, v8, v9
	v_cndmask_b32_e64 v236, v236, v249, s[0:1]
	v_cndmask_b32_e64 v237, v237, v249, s[0:1]
	v_cndmask_b32_e32 v240, v2, v248, vcc
	v_cndmask_b32_e32 v241, v3, v248, vcc
	v_cndmask_b32_e32 v242, v4, v248, vcc
	v_cndmask_b32_e32 v243, v5, v248, vcc
	v_cvt_pk_bf16_f32 v222, v240, v241
	v_cvt_pk_bf16_f32 v223, v242, v243
	v_pk_mul_f32 v[2:3], v[2:3], v[244:245] op_sel:[0,1]
	v_pk_mul_f32 v[4:5], v[4:5], v[244:245] op_sel:[0,1]
	v_pk_fma_f32 v[2:3], v[130:131], v[2:3], v[134:135]
	v_pk_fma_f32 v[4:5], v[132:133], v[4:5], v[136:137]
	v_cvt_pk_bf16_f32 v238, v2, v3
	v_cvt_pk_bf16_f32 v239, v4, v5
	v_cndmask_b32_e64 v238, v238, v249, s[0:1]
	v_cndmask_b32_e64 v239, v239, v249, s[0:1]
	v_permlane16_swap_b32_e32 v220, v222
	v_permlane16_swap_b32_e32 v221, v223
	s_nop 1
	v_permlane16_swap_b32_e32 v236, v238
	v_permlane16_swap_b32_e32 v237, v239
	global_store_dwordx4 v247, v[220:223], s[56:57] offset:256 sc1 nt
	global_store_dwordx4 v247, v[236:239], s[58:59] offset:256 sc1

.LBB0_936:
	s_or_b64 exec, exec, s[6:7]
	s_waitcnt lgkmcnt(1)
	v_add_co_u32_e32 v132, vcc, 0x108000, v148
	s_mov_b64 s[0:1], 0x108000
	s_nop 0
	v_addc_co_u32_e32 v133, vcc, 0, v149, vcc
	v_lshl_add_u64 v[130:131], v[148:149], 0, s[0:1]
	s_mov_b64 s[0:1], 0x10a000
	v_add_co_u32_e32 v136, vcc, 0x10a000, v148
	s_waitcnt lgkmcnt(0)
	s_barrier
	v_lshl_add_u64 v[134:135], v[148:149], 0, s[0:1]
	v_addc_co_u32_e32 v137, vcc, 0, v149, vcc
	global_load_dwordx4 v[146:149], v[134:135], off offset:64
	global_load_dwordx4 v[150:153], v[130:131], off offset:64
	global_load_dwordx4 v[138:141], v[130:131], off offset:512
	global_load_dwordx4 v[142:145], v[134:135], off offset:512
	global_load_dwordx4 v[154:157], v[132:133], off
	global_load_dwordx4 v[158:161], v[136:137], off
	s_nop 0
	global_load_dwordx4 v[130:133], v[130:131], off offset:576
	s_nop 0
	global_load_dwordx4 v[134:137], v[134:135], off offset:576
	v_or_b32_e32 v224, v186, v184
	s_waitcnt lgkmcnt(0)
	v_or_b32_e32 v225, v188, v224
	v_mov_b32_e32 v248, 0x7fc00000
	v_mov_b32_e32 v249, 0x7fc07fc0
	v_cmp_ne_u32_e32 vcc, 0, v224
	v_cmp_ne_u32_e64 s[0:1], 0, v225
	v_add_u32_e32 v246, v180, v162
	v_lshlrev_b32_e32 v246, 1, v246
	v_and_b32_e32 v247, 16, v0
	v_lshrrev_b32_e32 v247, 1, v247
	v_mad_u32_u24 v246, v247, 3, v246
	s_waitcnt vmcnt(0)
	ds_read_b64 v[244:245], v185 offset:8192
	s_waitcnt lgkmcnt(0)
	v_cndmask_b32_e32 v240, v118, v248, vcc
	v_cndmask_b32_e32 v241, v119, v248, vcc
	v_cndmask_b32_e32 v242, v120, v248, vcc
	v_cndmask_b32_e32 v243, v121, v248, vcc
	v_cvt_pk_bf16_f32 v216, v240, v241
	v_cvt_pk_bf16_f32 v217, v242, v243
	v_pk_mul_f32 v[118:119], v[118:119], v[244:245] op_sel:[0,1]
	v_pk_mul_f32 v[120:121], v[120:121], v[244:245] op_sel:[0,1]
	v_pk_fma_f32 v[118:119], v[154:155], v[118:119], v[158:159]
	v_pk_fma_f32 v[120:121], v[156:157], v[120:121], v[160:161]
	v_cvt_pk_bf16_f32 v232, v118, v119
	v_cvt_pk_bf16_f32 v233, v120, v121
	v_cndmask_b32_e64 v232, v232, v249, s[0:1]
	v_cndmask_b32_e64 v233, v233, v249, s[0:1]
	v_cndmask_b32_e32 v240, v122, v248, vcc
	v_cndmask_b32_e32 v241, v123, v248, vcc
	v_cndmask_b32_e32 v242, v124, v248, vcc
	v_cndmask_b32_e32 v243, v125, v248, vcc
	v_cvt_pk_bf16_f32 v218, v240, v241
	v_cvt_pk_bf16_f32 v219, v242, v243
	v_pk_mul_f32 v[122:123], v[122:123], v[244:245] op_sel:[0,1]
	v_pk_mul_f32 v[124:125], v[124:125], v[244:245] op_sel:[0,1]
	v_pk_fma_f32 v[122:123], v[150:151], v[122:123], v[146:147]
	v_pk_fma_f32 v[124:125], v[152:153], v[124:125], v[148:149]
	v_cvt_pk_bf16_f32 v234, v122, v123
	v_cvt_pk_bf16_f32 v235, v124, v125
	v_cndmask_b32_e64 v234, v234, v249, s[0:1]
	v_cndmask_b32_e64 v235, v235, v249, s[0:1]
	v_permlane16_swap_b32_e32 v216, v218
	v_permlane16_swap_b32_e32 v217, v219
	s_nop 1
	v_permlane16_swap_b32_e32 v232, v234
	v_permlane16_swap_b32_e32 v233, v235
	global_store_dwordx4 v246, v[216:219], s[94:95] sc1 nt
	global_store_dwordx4 v246, v[232:235], s[58:59] sc1
	v_cndmask_b32_e32 v240, v126, v248, vcc
	v_cndmask_b32_e32 v241, v127, v248, vcc
	v_cndmask_b32_e32 v242, v128, v248, vcc
	v_cndmask_b32_e32 v243, v129, v248, vcc
	v_cvt_pk_bf16_f32 v220, v240, v241
	v_cvt_pk_bf16_f32 v221, v242, v243
	v_pk_mul_f32 v[126:127], v[126:127], v[244:245] op_sel:[0,1]
	v_pk_mul_f32 v[128:129], v[128:129], v[244:245] op_sel:[0,1]
	v_pk_fma_f32 v[126:127], v[138:139], v[126:127], v[142:143]
	v_pk_fma_f32 v[128:129], v[140:141], v[128:129], v[144:145]
	v_cvt_pk_bf16_f32 v236, v126, v127
	v_cvt_pk_bf16_f32 v237, v128, v129
	v_cndmask_b32_e64 v236, v236, v249, s[0:1]
	v_cndmask_b32_e64 v237, v237, v249, s[0:1]
	v_cndmask_b32_e32 v240, v114, v248, vcc
	v_cndmask_b32_e32 v241, v115, v248, vcc
	v_cndmask_b32_e32 v242, v116, v248, vcc
	v_cndmask_b32_e32 v243, v117, v248, vcc
	v_cvt_pk_bf16_f32 v222, v240, v241
	v_cvt_pk_bf16_f32 v223, v242, v243
	v_pk_mul_f32 v[114:115], v[114:115], v[244:245] op_sel:[0,1]
	v_pk_mul_f32 v[116:117], v[116:117], v[244:245] op_sel:[0,1]
	v_pk_fma_f32 v[114:115], v[130:131], v[114:115], v[134:135]
	v_pk_fma_f32 v[116:117], v[132:133], v[116:117], v[136:137]
	v_cvt_pk_bf16_f32 v238, v114, v115
	v_cvt_pk_bf16_f32 v239, v116, v117
	v_cndmask_b32_e64 v238, v238, v249, s[0:1]
	v_cndmask_b32_e64 v239, v239, v249, s[0:1]
	v_permlane16_swap_b32_e32 v220, v222
	v_permlane16_swap_b32_e32 v221, v223
	s_nop 1
	v_permlane16_swap_b32_e32 v236, v238
	v_permlane16_swap_b32_e32 v237, v239
	global_store_dwordx4 v246, v[220:223], s[94:95] offset:256 sc1 nt
	global_store_dwordx4 v246, v[236:239], s[58:59] offset:256 sc1
	ds_read_b64 v[244:245], v185 offset:8320
	v_add_u32_e32 v247, 0x8000, v246
	s_waitcnt lgkmcnt(0)
	v_cndmask_b32_e32 v240, v110, v248, vcc
	v_cndmask_b32_e32 v241, v111, v248, vcc
	v_cndmask_b32_e32 v242, v112, v248, vcc
	v_cndmask_b32_e32 v243, v113, v248, vcc
	v_cvt_pk_bf16_f32 v216, v240, v241
	v_cvt_pk_bf16_f32 v217, v242, v243
	v_pk_mul_f32 v[110:111], v[110:111], v[244:245] op_sel:[0,1]
	v_pk_mul_f32 v[112:113], v[112:113], v[244:245] op_sel:[0,1]
	v_pk_fma_f32 v[110:111], v[154:155], v[110:111], v[158:159]
	v_pk_fma_f32 v[112:113], v[156:157], v[112:113], v[160:161]
	v_cvt_pk_bf16_f32 v232, v110, v111
	v_cvt_pk_bf16_f32 v233, v112, v113
	v_cndmask_b32_e64 v232, v232, v249, s[0:1]
	v_cndmask_b32_e64 v233, v233, v249, s[0:1]
	v_cndmask_b32_e32 v240, v106, v248, vcc
	v_cndmask_b32_e32 v241, v107, v248, vcc
	v_cndmask_b32_e32 v242, v108, v248, vcc
	v_cndmask_b32_e32 v243, v109, v248, vcc
	v_cvt_pk_bf16_f32 v218, v240, v241
	v_cvt_pk_bf16_f32 v219, v242, v243
	v_pk_mul_f32 v[106:107], v[106:107], v[244:245] op_sel:[0,1]
	v_pk_mul_f32 v[108:109], v[108:109], v[244:245] op_sel:[0,1]
	v_pk_fma_f32 v[106:107], v[150:151], v[106:107], v[146:147]
	v_pk_fma_f32 v[108:109], v[152:153], v[108:109], v[148:149]
	v_cvt_pk_bf16_f32 v234, v106, v107
	v_cvt_pk_bf16_f32 v235, v108, v109
	v_cndmask_b32_e64 v234, v234, v249, s[0:1]
	v_cndmask_b32_e64 v235, v235, v249, s[0:1]
	v_permlane16_swap_b32_e32 v216, v218
	v_permlane16_swap_b32_e32 v217, v219
	s_nop 1
	v_permlane16_swap_b32_e32 v232, v234
	v_permlane16_swap_b32_e32 v233, v235
	global_store_dwordx4 v247, v[216:219], s[94:95] sc1 nt
	global_store_dwordx4 v247, v[232:235], s[58:59] sc1
	v_cndmask_b32_e32 v240, v102, v248, vcc
	v_cndmask_b32_e32 v241, v103, v248, vcc
	v_cndmask_b32_e32 v242, v104, v248, vcc
	v_cndmask_b32_e32 v243, v105, v248, vcc
	v_cvt_pk_bf16_f32 v220, v240, v241
	v_cvt_pk_bf16_f32 v221, v242, v243
	v_pk_mul_f32 v[102:103], v[102:103], v[244:245] op_sel:[0,1]
	v_pk_mul_f32 v[104:105], v[104:105], v[244:245] op_sel:[0,1]
	v_pk_fma_f32 v[102:103], v[138:139], v[102:103], v[142:143]
	v_pk_fma_f32 v[104:105], v[140:141], v[104:105], v[144:145]
	v_cvt_pk_bf16_f32 v236, v102, v103
	v_cvt_pk_bf16_f32 v237, v104, v105
	v_cndmask_b32_e64 v236, v236, v249, s[0:1]
	v_cndmask_b32_e64 v237, v237, v249, s[0:1]
	v_cndmask_b32_e32 v240, v98, v248, vcc
	v_cndmask_b32_e32 v241, v99, v248, vcc
	v_cndmask_b32_e32 v242, v100, v248, vcc
	v_cndmask_b32_e32 v243, v101, v248, vcc
	v_cvt_pk_bf16_f32 v222, v240, v241
	v_cvt_pk_bf16_f32 v223, v242, v243
	v_pk_mul_f32 v[98:99], v[98:99], v[244:245] op_sel:[0,1]
	v_pk_mul_f32 v[100:101], v[100:101], v[244:245] op_sel:[0,1]
	v_pk_fma_f32 v[98:99], v[130:131], v[98:99], v[134:135]
	v_pk_fma_f32 v[100:101], v[132:133], v[100:101], v[136:137]
	v_cvt_pk_bf16_f32 v238, v98, v99
	v_cvt_pk_bf16_f32 v239, v100, v101
	v_cndmask_b32_e64 v238, v238, v249, s[0:1]
	v_cndmask_b32_e64 v239, v239, v249, s[0:1]
	v_permlane16_swap_b32_e32 v220, v222
	v_permlane16_swap_b32_e32 v221, v223
	s_nop 1
	v_permlane16_swap_b32_e32 v236, v238
	v_permlane16_swap_b32_e32 v237, v239
	global_store_dwordx4 v247, v[220:223], s[94:95] offset:256 sc1 nt
	global_store_dwordx4 v247, v[236:239], s[58:59] offset:256 sc1
	ds_read_b64 v[244:245], v185 offset:8448
	v_add_u32_e32 v247, 0x10000, v246
	s_waitcnt lgkmcnt(0)
	v_cndmask_b32_e32 v240, v94, v248, vcc
	v_cndmask_b32_e32 v241, v95, v248, vcc
	v_cndmask_b32_e32 v242, v96, v248, vcc
	v_cndmask_b32_e32 v243, v97, v248, vcc
	v_cvt_pk_bf16_f32 v216, v240, v241
	v_cvt_pk_bf16_f32 v217, v242, v243
	v_pk_mul_f32 v[94:95], v[94:95], v[244:245] op_sel:[0,1]
	v_pk_mul_f32 v[96:97], v[96:97], v[244:245] op_sel:[0,1]
	v_pk_fma_f32 v[94:95], v[154:155], v[94:95], v[158:159]
	v_pk_fma_f32 v[96:97], v[156:157], v[96:97], v[160:161]
	v_cvt_pk_bf16_f32 v232, v94, v95
	v_cvt_pk_bf16_f32 v233, v96, v97
	v_cndmask_b32_e64 v232, v232, v249, s[0:1]
	v_cndmask_b32_e64 v233, v233, v249, s[0:1]
	v_cndmask_b32_e32 v240, v90, v248, vcc
	v_cndmask_b32_e32 v241, v91, v248, vcc
	v_cndmask_b32_e32 v242, v92, v248, vcc
	v_cndmask_b32_e32 v243, v93, v248, vcc
	v_cvt_pk_bf16_f32 v218, v240, v241
	v_cvt_pk_bf16_f32 v219, v242, v243
	v_pk_mul_f32 v[90:91], v[90:91], v[244:245] op_sel:[0,1]
	v_pk_mul_f32 v[92:93], v[92:93], v[244:245] op_sel:[0,1]
	v_pk_fma_f32 v[90:91], v[150:151], v[90:91], v[146:147]
	v_pk_fma_f32 v[92:93], v[152:153], v[92:93], v[148:149]
	v_cvt_pk_bf16_f32 v234, v90, v91
	v_cvt_pk_bf16_f32 v235, v92, v93
	v_cndmask_b32_e64 v234, v234, v249, s[0:1]
	v_cndmask_b32_e64 v235, v235, v249, s[0:1]
	v_permlane16_swap_b32_e32 v216, v218
	v_permlane16_swap_b32_e32 v217, v219
	s_nop 1
	v_permlane16_swap_b32_e32 v232, v234
	v_permlane16_swap_b32_e32 v233, v235
	global_store_dwordx4 v247, v[216:219], s[94:95] sc1 nt
	global_store_dwordx4 v247, v[232:235], s[58:59] sc1
	v_cndmask_b32_e32 v240, v86, v248, vcc
	v_cndmask_b32_e32 v241, v87, v248, vcc
	v_cndmask_b32_e32 v242, v88, v248, vcc
	v_cndmask_b32_e32 v243, v89, v248, vcc
	v_cvt_pk_bf16_f32 v220, v240, v241
	v_cvt_pk_bf16_f32 v221, v242, v243
	v_pk_mul_f32 v[86:87], v[86:87], v[244:245] op_sel:[0,1]
	v_pk_mul_f32 v[88:89], v[88:89], v[244:245] op_sel:[0,1]
	v_pk_fma_f32 v[86:87], v[138:139], v[86:87], v[142:143]
	v_pk_fma_f32 v[88:89], v[140:141], v[88:89], v[144:145]
	v_cvt_pk_bf16_f32 v236, v86, v87
	v_cvt_pk_bf16_f32 v237, v88, v89
	v_cndmask_b32_e64 v236, v236, v249, s[0:1]
	v_cndmask_b32_e64 v237, v237, v249, s[0:1]
	v_cndmask_b32_e32 v240, v82, v248, vcc
	v_cndmask_b32_e32 v241, v83, v248, vcc
	v_cndmask_b32_e32 v242, v84, v248, vcc
	v_cndmask_b32_e32 v243, v85, v248, vcc
	v_cvt_pk_bf16_f32 v222, v240, v241
	v_cvt_pk_bf16_f32 v223, v242, v243
	v_pk_mul_f32 v[82:83], v[82:83], v[244:245] op_sel:[0,1]
	v_pk_mul_f32 v[84:85], v[84:85], v[244:245] op_sel:[0,1]
	v_pk_fma_f32 v[82:83], v[130:131], v[82:83], v[134:135]
	v_pk_fma_f32 v[84:85], v[132:133], v[84:85], v[136:137]
	v_cvt_pk_bf16_f32 v238, v82, v83
	v_cvt_pk_bf16_f32 v239, v84, v85
	v_cndmask_b32_e64 v238, v238, v249, s[0:1]
	v_cndmask_b32_e64 v239, v239, v249, s[0:1]
	v_permlane16_swap_b32_e32 v220, v222
	v_permlane16_swap_b32_e32 v221, v223
	s_nop 1
	v_permlane16_swap_b32_e32 v236, v238
	v_permlane16_swap_b32_e32 v237, v239
	global_store_dwordx4 v247, v[220:223], s[94:95] offset:256 sc1 nt
	global_store_dwordx4 v247, v[236:239], s[58:59] offset:256 sc1
	ds_read_b64 v[244:245], v185 offset:8576
	v_add_u32_e32 v247, 0x18000, v246
	s_waitcnt lgkmcnt(0)
	v_cndmask_b32_e32 v240, v78, v248, vcc
	v_cndmask_b32_e32 v241, v79, v248, vcc
	v_cndmask_b32_e32 v242, v80, v248, vcc
	v_cndmask_b32_e32 v243, v81, v248, vcc
	v_cvt_pk_bf16_f32 v216, v240, v241
	v_cvt_pk_bf16_f32 v217, v242, v243
	v_pk_mul_f32 v[78:79], v[78:79], v[244:245] op_sel:[0,1]
	v_pk_mul_f32 v[80:81], v[80:81], v[244:245] op_sel:[0,1]
	v_pk_fma_f32 v[78:79], v[154:155], v[78:79], v[158:159]
	v_pk_fma_f32 v[80:81], v[156:157], v[80:81], v[160:161]
	v_cvt_pk_bf16_f32 v232, v78, v79
	v_cvt_pk_bf16_f32 v233, v80, v81
	v_cndmask_b32_e64 v232, v232, v249, s[0:1]
	v_cndmask_b32_e64 v233, v233, v249, s[0:1]
	v_cndmask_b32_e32 v240, v74, v248, vcc
	v_cndmask_b32_e32 v241, v75, v248, vcc
	v_cndmask_b32_e32 v242, v76, v248, vcc
	v_cndmask_b32_e32 v243, v77, v248, vcc
	v_cvt_pk_bf16_f32 v218, v240, v241
	v_cvt_pk_bf16_f32 v219, v242, v243
	v_pk_mul_f32 v[74:75], v[74:75], v[244:245] op_sel:[0,1]
	v_pk_mul_f32 v[76:77], v[76:77], v[244:245] op_sel:[0,1]
	v_pk_fma_f32 v[74:75], v[150:151], v[74:75], v[146:147]
	v_pk_fma_f32 v[76:77], v[152:153], v[76:77], v[148:149]
	v_cvt_pk_bf16_f32 v234, v74, v75
	v_cvt_pk_bf16_f32 v235, v76, v77
	v_cndmask_b32_e64 v234, v234, v249, s[0:1]
	v_cndmask_b32_e64 v235, v235, v249, s[0:1]
	v_permlane16_swap_b32_e32 v216, v218
	v_permlane16_swap_b32_e32 v217, v219
	s_nop 1
	v_permlane16_swap_b32_e32 v232, v234
	v_permlane16_swap_b32_e32 v233, v235
	global_store_dwordx4 v247, v[216:219], s[94:95] sc1 nt
	global_store_dwordx4 v247, v[232:235], s[58:59] sc1
	v_cndmask_b32_e32 v240, v70, v248, vcc
	v_cndmask_b32_e32 v241, v71, v248, vcc
	v_cndmask_b32_e32 v242, v72, v248, vcc
	v_cndmask_b32_e32 v243, v73, v248, vcc
	v_cvt_pk_bf16_f32 v220, v240, v241
	v_cvt_pk_bf16_f32 v221, v242, v243
	v_pk_mul_f32 v[70:71], v[70:71], v[244:245] op_sel:[0,1]
	v_pk_mul_f32 v[72:73], v[72:73], v[244:245] op_sel:[0,1]
	v_pk_fma_f32 v[70:71], v[138:139], v[70:71], v[142:143]
	v_pk_fma_f32 v[72:73], v[140:141], v[72:73], v[144:145]
	v_cvt_pk_bf16_f32 v236, v70, v71
	v_cvt_pk_bf16_f32 v237, v72, v73
	v_cndmask_b32_e64 v236, v236, v249, s[0:1]
	v_cndmask_b32_e64 v237, v237, v249, s[0:1]
	v_cndmask_b32_e32 v240, v66, v248, vcc
	v_cndmask_b32_e32 v241, v67, v248, vcc
	v_cndmask_b32_e32 v242, v68, v248, vcc
	v_cndmask_b32_e32 v243, v69, v248, vcc
	v_cvt_pk_bf16_f32 v222, v240, v241
	v_cvt_pk_bf16_f32 v223, v242, v243
	v_pk_mul_f32 v[66:67], v[66:67], v[244:245] op_sel:[0,1]
	v_pk_mul_f32 v[68:69], v[68:69], v[244:245] op_sel:[0,1]
	v_pk_fma_f32 v[66:67], v[130:131], v[66:67], v[134:135]
	v_pk_fma_f32 v[68:69], v[132:133], v[68:69], v[136:137]
	v_cvt_pk_bf16_f32 v238, v66, v67
	v_cvt_pk_bf16_f32 v239, v68, v69
	v_cndmask_b32_e64 v238, v238, v249, s[0:1]
	v_cndmask_b32_e64 v239, v239, v249, s[0:1]
	v_permlane16_swap_b32_e32 v220, v222
	v_permlane16_swap_b32_e32 v221, v223
	s_nop 1
	v_permlane16_swap_b32_e32 v236, v238
	v_permlane16_swap_b32_e32 v237, v239
	global_store_dwordx4 v247, v[220:223], s[94:95] offset:256 sc1 nt
	global_store_dwordx4 v247, v[236:239], s[58:59] offset:256 sc1
	ds_read_b64 v[244:245], v185 offset:9216
	v_add_u32_e32 v247, 0x40000, v246
	s_waitcnt lgkmcnt(0)
	v_cndmask_b32_e32 v240, v62, v248, vcc
	v_cndmask_b32_e32 v241, v63, v248, vcc
	v_cndmask_b32_e32 v242, v64, v248, vcc
	v_cndmask_b32_e32 v243, v65, v248, vcc
	v_cvt_pk_bf16_f32 v216, v240, v241
	v_cvt_pk_bf16_f32 v217, v242, v243
	v_pk_mul_f32 v[62:63], v[62:63], v[244:245] op_sel:[0,1]
	v_pk_mul_f32 v[64:65], v[64:65], v[244:245] op_sel:[0,1]
	v_pk_fma_f32 v[62:63], v[154:155], v[62:63], v[158:159]
	v_pk_fma_f32 v[64:65], v[156:157], v[64:65], v[160:161]
	v_cvt_pk_bf16_f32 v232, v62, v63
	v_cvt_pk_bf16_f32 v233, v64, v65
	v_cndmask_b32_e64 v232, v232, v249, s[0:1]
	v_cndmask_b32_e64 v233, v233, v249, s[0:1]
	v_cndmask_b32_e32 v240, v58, v248, vcc
	v_cndmask_b32_e32 v241, v59, v248, vcc
	v_cndmask_b32_e32 v242, v60, v248, vcc
	v_cndmask_b32_e32 v243, v61, v248, vcc
	v_cvt_pk_bf16_f32 v218, v240, v241
	v_cvt_pk_bf16_f32 v219, v242, v243
	v_pk_mul_f32 v[58:59], v[58:59], v[244:245] op_sel:[0,1]
	v_pk_mul_f32 v[60:61], v[60:61], v[244:245] op_sel:[0,1]
	v_pk_fma_f32 v[58:59], v[150:151], v[58:59], v[146:147]
	v_pk_fma_f32 v[60:61], v[152:153], v[60:61], v[148:149]
	v_cvt_pk_bf16_f32 v234, v58, v59
	v_cvt_pk_bf16_f32 v235, v60, v61
	v_cndmask_b32_e64 v234, v234, v249, s[0:1]
	v_cndmask_b32_e64 v235, v235, v249, s[0:1]
	v_permlane16_swap_b32_e32 v216, v218
	v_permlane16_swap_b32_e32 v217, v219
	s_nop 1
	v_permlane16_swap_b32_e32 v232, v234
	v_permlane16_swap_b32_e32 v233, v235
	global_store_dwordx4 v247, v[216:219], s[94:95] sc1 nt
	global_store_dwordx4 v247, v[232:235], s[58:59] sc1
	v_cndmask_b32_e32 v240, v54, v248, vcc
	v_cndmask_b32_e32 v241, v55, v248, vcc
	v_cndmask_b32_e32 v242, v56, v248, vcc
	v_cndmask_b32_e32 v243, v57, v248, vcc
	v_cvt_pk_bf16_f32 v220, v240, v241
	v_cvt_pk_bf16_f32 v221, v242, v243
	v_pk_mul_f32 v[54:55], v[54:55], v[244:245] op_sel:[0,1]
	v_pk_mul_f32 v[56:57], v[56:57], v[244:245] op_sel:[0,1]
	v_pk_fma_f32 v[54:55], v[138:139], v[54:55], v[142:143]
	v_pk_fma_f32 v[56:57], v[140:141], v[56:57], v[144:145]
	v_cvt_pk_bf16_f32 v236, v54, v55
	v_cvt_pk_bf16_f32 v237, v56, v57
	v_cndmask_b32_e64 v236, v236, v249, s[0:1]
	v_cndmask_b32_e64 v237, v237, v249, s[0:1]
	v_cndmask_b32_e32 v240, v50, v248, vcc
	v_cndmask_b32_e32 v241, v51, v248, vcc
	v_cndmask_b32_e32 v242, v52, v248, vcc
	v_cndmask_b32_e32 v243, v53, v248, vcc
	v_cvt_pk_bf16_f32 v222, v240, v241
	v_cvt_pk_bf16_f32 v223, v242, v243
	v_pk_mul_f32 v[50:51], v[50:51], v[244:245] op_sel:[0,1]
	v_pk_mul_f32 v[52:53], v[52:53], v[244:245] op_sel:[0,1]
	v_pk_fma_f32 v[50:51], v[130:131], v[50:51], v[134:135]
	v_pk_fma_f32 v[52:53], v[132:133], v[52:53], v[136:137]
	v_cvt_pk_bf16_f32 v238, v50, v51
	v_cvt_pk_bf16_f32 v239, v52, v53
	v_cndmask_b32_e64 v238, v238, v249, s[0:1]
	v_cndmask_b32_e64 v239, v239, v249, s[0:1]
	v_permlane16_swap_b32_e32 v220, v222
	v_permlane16_swap_b32_e32 v221, v223
	s_nop 1
	v_permlane16_swap_b32_e32 v236, v238
	v_permlane16_swap_b32_e32 v237, v239
	global_store_dwordx4 v247, v[220:223], s[94:95] offset:256 sc1 nt
	global_store_dwordx4 v247, v[236:239], s[58:59] offset:256 sc1
	ds_read_b64 v[244:245], v185 offset:9344
	v_add_u32_e32 v247, 0x48000, v246
	s_waitcnt lgkmcnt(0)
	v_cndmask_b32_e32 v240, v46, v248, vcc
	v_cndmask_b32_e32 v241, v47, v248, vcc
	v_cndmask_b32_e32 v242, v48, v248, vcc
	v_cndmask_b32_e32 v243, v49, v248, vcc
	v_cvt_pk_bf16_f32 v216, v240, v241
	v_cvt_pk_bf16_f32 v217, v242, v243
	v_pk_mul_f32 v[46:47], v[46:47], v[244:245] op_sel:[0,1]
	v_pk_mul_f32 v[48:49], v[48:49], v[244:245] op_sel:[0,1]
	v_pk_fma_f32 v[46:47], v[154:155], v[46:47], v[158:159]
	v_pk_fma_f32 v[48:49], v[156:157], v[48:49], v[160:161]
	v_cvt_pk_bf16_f32 v232, v46, v47
	v_cvt_pk_bf16_f32 v233, v48, v49
	v_cndmask_b32_e64 v232, v232, v249, s[0:1]
	v_cndmask_b32_e64 v233, v233, v249, s[0:1]
	v_cndmask_b32_e32 v240, v42, v248, vcc
	v_cndmask_b32_e32 v241, v43, v248, vcc
	v_cndmask_b32_e32 v242, v44, v248, vcc
	v_cndmask_b32_e32 v243, v45, v248, vcc
	v_cvt_pk_bf16_f32 v218, v240, v241
	v_cvt_pk_bf16_f32 v219, v242, v243
	v_pk_mul_f32 v[42:43], v[42:43], v[244:245] op_sel:[0,1]
	v_pk_mul_f32 v[44:45], v[44:45], v[244:245] op_sel:[0,1]
	v_pk_fma_f32 v[42:43], v[150:151], v[42:43], v[146:147]
	v_pk_fma_f32 v[44:45], v[152:153], v[44:45], v[148:149]
	v_cvt_pk_bf16_f32 v234, v42, v43
	v_cvt_pk_bf16_f32 v235, v44, v45
	v_cndmask_b32_e64 v234, v234, v249, s[0:1]
	v_cndmask_b32_e64 v235, v235, v249, s[0:1]
	v_permlane16_swap_b32_e32 v216, v218
	v_permlane16_swap_b32_e32 v217, v219
	s_nop 1
	v_permlane16_swap_b32_e32 v232, v234
	v_permlane16_swap_b32_e32 v233, v235
	global_store_dwordx4 v247, v[216:219], s[94:95] sc1 nt
	global_store_dwordx4 v247, v[232:235], s[58:59] sc1
	v_cndmask_b32_e32 v240, v38, v248, vcc
	v_cndmask_b32_e32 v241, v39, v248, vcc
	v_cndmask_b32_e32 v242, v40, v248, vcc
	v_cndmask_b32_e32 v243, v41, v248, vcc
	v_cvt_pk_bf16_f32 v220, v240, v241
	v_cvt_pk_bf16_f32 v221, v242, v243
	v_pk_mul_f32 v[38:39], v[38:39], v[244:245] op_sel:[0,1]
	v_pk_mul_f32 v[40:41], v[40:41], v[244:245] op_sel:[0,1]
	v_pk_fma_f32 v[38:39], v[138:139], v[38:39], v[142:143]
	v_pk_fma_f32 v[40:41], v[140:141], v[40:41], v[144:145]
	v_cvt_pk_bf16_f32 v236, v38, v39
	v_cvt_pk_bf16_f32 v237, v40, v41
	v_cndmask_b32_e64 v236, v236, v249, s[0:1]
	v_cndmask_b32_e64 v237, v237, v249, s[0:1]
	v_cndmask_b32_e32 v240, v34, v248, vcc
	v_cndmask_b32_e32 v241, v35, v248, vcc
	v_cndmask_b32_e32 v242, v36, v248, vcc
	v_cndmask_b32_e32 v243, v37, v248, vcc
	v_cvt_pk_bf16_f32 v222, v240, v241
	v_cvt_pk_bf16_f32 v223, v242, v243
	v_pk_mul_f32 v[34:35], v[34:35], v[244:245] op_sel:[0,1]
	v_pk_mul_f32 v[36:37], v[36:37], v[244:245] op_sel:[0,1]
	v_pk_fma_f32 v[34:35], v[130:131], v[34:35], v[134:135]
	v_pk_fma_f32 v[36:37], v[132:133], v[36:37], v[136:137]
	v_cvt_pk_bf16_f32 v238, v34, v35
	v_cvt_pk_bf16_f32 v239, v36, v37
	v_cndmask_b32_e64 v238, v238, v249, s[0:1]
	v_cndmask_b32_e64 v239, v239, v249, s[0:1]
	v_permlane16_swap_b32_e32 v220, v222
	v_permlane16_swap_b32_e32 v221, v223
	s_nop 1
	v_permlane16_swap_b32_e32 v236, v238
	v_permlane16_swap_b32_e32 v237, v239
	global_store_dwordx4 v247, v[220:223], s[94:95] offset:256 sc1 nt
	global_store_dwordx4 v247, v[236:239], s[58:59] offset:256 sc1
	ds_read_b64 v[244:245], v185 offset:9472
	v_add_u32_e32 v247, 0x50000, v246
	s_waitcnt lgkmcnt(0)
	v_cndmask_b32_e32 v240, v30, v248, vcc
	v_cndmask_b32_e32 v241, v31, v248, vcc
	v_cndmask_b32_e32 v242, v32, v248, vcc
	v_cndmask_b32_e32 v243, v33, v248, vcc
	v_cvt_pk_bf16_f32 v216, v240, v241
	v_cvt_pk_bf16_f32 v217, v242, v243
	v_pk_mul_f32 v[30:31], v[30:31], v[244:245] op_sel:[0,1]
	v_pk_mul_f32 v[32:33], v[32:33], v[244:245] op_sel:[0,1]
	v_pk_fma_f32 v[30:31], v[154:155], v[30:31], v[158:159]
	v_pk_fma_f32 v[32:33], v[156:157], v[32:33], v[160:161]
	v_cvt_pk_bf16_f32 v232, v30, v31
	v_cvt_pk_bf16_f32 v233, v32, v33
	v_cndmask_b32_e64 v232, v232, v249, s[0:1]
	v_cndmask_b32_e64 v233, v233, v249, s[0:1]
	v_cndmask_b32_e32 v240, v26, v248, vcc
	v_cndmask_b32_e32 v241, v27, v248, vcc
	v_cndmask_b32_e32 v242, v28, v248, vcc
	v_cndmask_b32_e32 v243, v29, v248, vcc
	v_cvt_pk_bf16_f32 v218, v240, v241
	v_cvt_pk_bf16_f32 v219, v242, v243
	v_pk_mul_f32 v[26:27], v[26:27], v[244:245] op_sel:[0,1]
	v_pk_mul_f32 v[28:29], v[28:29], v[244:245] op_sel:[0,1]
	v_pk_fma_f32 v[26:27], v[150:151], v[26:27], v[146:147]
	v_pk_fma_f32 v[28:29], v[152:153], v[28:29], v[148:149]
	v_cvt_pk_bf16_f32 v234, v26, v27
	v_cvt_pk_bf16_f32 v235, v28, v29
	v_cndmask_b32_e64 v234, v234, v249, s[0:1]
	v_cndmask_b32_e64 v235, v235, v249, s[0:1]
	v_permlane16_swap_b32_e32 v216, v218
	v_permlane16_swap_b32_e32 v217, v219
	s_nop 1
	v_permlane16_swap_b32_e32 v232, v234
	v_permlane16_swap_b32_e32 v233, v235
	global_store_dwordx4 v247, v[216:219], s[94:95] sc1 nt
	global_store_dwordx4 v247, v[232:235], s[58:59] sc1
	v_cndmask_b32_e32 v240, v22, v248, vcc
	v_cndmask_b32_e32 v241, v23, v248, vcc
	v_cndmask_b32_e32 v242, v24, v248, vcc
	v_cndmask_b32_e32 v243, v25, v248, vcc
	v_cvt_pk_bf16_f32 v220, v240, v241
	v_cvt_pk_bf16_f32 v221, v242, v243
	v_pk_mul_f32 v[22:23], v[22:23], v[244:245] op_sel:[0,1]
	v_pk_mul_f32 v[24:25], v[24:25], v[244:245] op_sel:[0,1]
	v_pk_fma_f32 v[22:23], v[138:139], v[22:23], v[142:143]
	v_pk_fma_f32 v[24:25], v[140:141], v[24:25], v[144:145]
	v_cvt_pk_bf16_f32 v236, v22, v23
	v_cvt_pk_bf16_f32 v237, v24, v25
	v_cndmask_b32_e64 v236, v236, v249, s[0:1]
	v_cndmask_b32_e64 v237, v237, v249, s[0:1]
	v_cndmask_b32_e32 v240, v18, v248, vcc
	v_cndmask_b32_e32 v241, v19, v248, vcc
	v_cndmask_b32_e32 v242, v20, v248, vcc
	v_cndmask_b32_e32 v243, v21, v248, vcc
	v_cvt_pk_bf16_f32 v222, v240, v241
	v_cvt_pk_bf16_f32 v223, v242, v243
	v_pk_mul_f32 v[18:19], v[18:19], v[244:245] op_sel:[0,1]
	v_pk_mul_f32 v[20:21], v[20:21], v[244:245] op_sel:[0,1]
	v_pk_fma_f32 v[18:19], v[130:131], v[18:19], v[134:135]
	v_pk_fma_f32 v[20:21], v[132:133], v[20:21], v[136:137]
	v_cvt_pk_bf16_f32 v238, v18, v19
	v_cvt_pk_bf16_f32 v239, v20, v21
	v_cndmask_b32_e64 v238, v238, v249, s[0:1]
	v_cndmask_b32_e64 v239, v239, v249, s[0:1]
	v_permlane16_swap_b32_e32 v220, v222
	v_permlane16_swap_b32_e32 v221, v223
	s_nop 1
	v_permlane16_swap_b32_e32 v236, v238
	v_permlane16_swap_b32_e32 v237, v239
	global_store_dwordx4 v247, v[220:223], s[94:95] offset:256 sc1 nt
	global_store_dwordx4 v247, v[236:239], s[58:59] offset:256 sc1
	ds_read_b64 v[244:245], v185 offset:9600
	v_add_u32_e32 v247, 0x58000, v246
	s_waitcnt lgkmcnt(0)
	v_cndmask_b32_e32 v240, v14, v248, vcc
	v_cndmask_b32_e32 v241, v15, v248, vcc
	v_cndmask_b32_e32 v242, v16, v248, vcc
	v_cndmask_b32_e32 v243, v17, v248, vcc
	v_cvt_pk_bf16_f32 v216, v240, v241
	v_cvt_pk_bf16_f32 v217, v242, v243
	v_pk_mul_f32 v[14:15], v[14:15], v[244:245] op_sel:[0,1]
	v_pk_mul_f32 v[16:17], v[16:17], v[244:245] op_sel:[0,1]
	v_pk_fma_f32 v[14:15], v[154:155], v[14:15], v[158:159]
	v_pk_fma_f32 v[16:17], v[156:157], v[16:17], v[160:161]
	v_cvt_pk_bf16_f32 v232, v14, v15
	v_cvt_pk_bf16_f32 v233, v16, v17
	v_cndmask_b32_e64 v232, v232, v249, s[0:1]
	v_cndmask_b32_e64 v233, v233, v249, s[0:1]
	v_cndmask_b32_e32 v240, v10, v248, vcc
	v_cndmask_b32_e32 v241, v11, v248, vcc
	v_cndmask_b32_e32 v242, v12, v248, vcc
	v_cndmask_b32_e32 v243, v13, v248, vcc
	v_cvt_pk_bf16_f32 v218, v240, v241
	v_cvt_pk_bf16_f32 v219, v242, v243
	v_pk_mul_f32 v[10:11], v[10:11], v[244:245] op_sel:[0,1]
	v_pk_mul_f32 v[12:13], v[12:13], v[244:245] op_sel:[0,1]
	v_pk_fma_f32 v[10:11], v[150:151], v[10:11], v[146:147]
	v_pk_fma_f32 v[12:13], v[152:153], v[12:13], v[148:149]
	v_cvt_pk_bf16_f32 v234, v10, v11
	v_cvt_pk_bf16_f32 v235, v12, v13
	v_cndmask_b32_e64 v234, v234, v249, s[0:1]
	v_cndmask_b32_e64 v235, v235, v249, s[0:1]
	v_permlane16_swap_b32_e32 v216, v218
	v_permlane16_swap_b32_e32 v217, v219
	s_nop 1
	v_permlane16_swap_b32_e32 v232, v234
	v_permlane16_swap_b32_e32 v233, v235
	global_store_dwordx4 v247, v[216:219], s[94:95] sc1 nt
	global_store_dwordx4 v247, v[232:235], s[58:59] sc1
	v_cndmask_b32_e32 v240, v6, v248, vcc
	v_cndmask_b32_e32 v241, v7, v248, vcc
	v_cndmask_b32_e32 v242, v8, v248, vcc
	v_cndmask_b32_e32 v243, v9, v248, vcc
	v_cvt_pk_bf16_f32 v220, v240, v241
	v_cvt_pk_bf16_f32 v221, v242, v243
	v_pk_mul_f32 v[6:7], v[6:7], v[244:245] op_sel:[0,1]
	v_pk_mul_f32 v[8:9], v[8:9], v[244:245] op_sel:[0,1]
	v_pk_fma_f32 v[6:7], v[138:139], v[6:7], v[142:143]
	v_pk_fma_f32 v[8:9], v[140:141], v[8:9], v[144:145]
	v_cvt_pk_bf16_f32 v236, v6, v7
	v_cvt_pk_bf16_f32 v237, v8, v9
	v_cndmask_b32_e64 v236, v236, v249, s[0:1]
	v_cndmask_b32_e64 v237, v237, v249, s[0:1]
	v_cndmask_b32_e32 v240, v2, v248, vcc
	v_cndmask_b32_e32 v241, v3, v248, vcc
	v_cndmask_b32_e32 v242, v4, v248, vcc
	v_cndmask_b32_e32 v243, v5, v248, vcc
	v_cvt_pk_bf16_f32 v222, v240, v241
	v_cvt_pk_bf16_f32 v223, v242, v243
	v_pk_mul_f32 v[2:3], v[2:3], v[244:245] op_sel:[0,1]
	v_pk_mul_f32 v[4:5], v[4:5], v[244:245] op_sel:[0,1]
	v_pk_fma_f32 v[2:3], v[130:131], v[2:3], v[134:135]
	v_pk_fma_f32 v[4:5], v[132:133], v[4:5], v[136:137]
	v_cvt_pk_bf16_f32 v238, v2, v3
	v_cvt_pk_bf16_f32 v239, v4, v5
	v_cndmask_b32_e64 v238, v238, v249, s[0:1]
	v_cndmask_b32_e64 v239, v239, v249, s[0:1]
	v_permlane16_swap_b32_e32 v220, v222
	v_permlane16_swap_b32_e32 v221, v223
	s_nop 1
	v_permlane16_swap_b32_e32 v236, v238
	v_permlane16_swap_b32_e32 v237, v239
	global_store_dwordx4 v247, v[220:223], s[94:95] offset:256 sc1 nt
	global_store_dwordx4 v247, v[236:239], s[58:59] offset:256 sc1

.LBB0_1531:
	s_or_b64 exec, exec, s[6:7]
	s_waitcnt lgkmcnt(1)
	v_add_co_u32_e32 v132, vcc, 0x10e000, v148
	s_mov_b64 s[0:1], 0x10e000
	s_nop 0
	v_addc_co_u32_e32 v133, vcc, 0, v149, vcc
	v_lshl_add_u64 v[130:131], v[148:149], 0, s[0:1]
	s_mov_b64 s[0:1], 0x110000
	v_add_co_u32_e32 v136, vcc, 0x110000, v148
	s_waitcnt lgkmcnt(0)
	s_barrier
	v_lshl_add_u64 v[134:135], v[148:149], 0, s[0:1]
	v_addc_co_u32_e32 v137, vcc, 0, v149, vcc
	global_load_dwordx4 v[146:149], v[134:135], off offset:64
	global_load_dwordx4 v[150:153], v[130:131], off offset:64
	global_load_dwordx4 v[138:141], v[130:131], off offset:512
	global_load_dwordx4 v[142:145], v[134:135], off offset:512
	global_load_dwordx4 v[154:157], v[132:133], off
	global_load_dwordx4 v[158:161], v[136:137], off
	s_nop 0
	global_load_dwordx4 v[130:133], v[130:131], off offset:576
	s_nop 0
	global_load_dwordx4 v[134:137], v[134:135], off offset:576
	v_or_b32_e32 v224, v184, v182
	s_waitcnt lgkmcnt(0)
	v_or_b32_e32 v225, v186, v224
	v_mov_b32_e32 v248, 0x7fc00000
	v_mov_b32_e32 v249, 0x7fc07fc0
	v_cmp_ne_u32_e32 vcc, 0, v224
	v_cmp_ne_u32_e64 s[0:1], 0, v225
	v_add_u32_e32 v246, v180, v162
	v_lshlrev_b32_e32 v246, 1, v246
	v_and_b32_e32 v247, 16, v0
	v_lshrrev_b32_e32 v247, 1, v247
	v_mad_u32_u24 v246, v247, 3, v246
	s_waitcnt vmcnt(0)
	ds_read_b64 v[244:245], v183 offset:8192
	s_waitcnt lgkmcnt(0)
	v_cndmask_b32_e32 v240, v118, v248, vcc
	v_cndmask_b32_e32 v241, v119, v248, vcc
	v_cndmask_b32_e32 v242, v120, v248, vcc
	v_cndmask_b32_e32 v243, v121, v248, vcc
	v_cvt_pk_bf16_f32 v216, v240, v241
	v_cvt_pk_bf16_f32 v217, v242, v243
	v_pk_mul_f32 v[118:119], v[118:119], v[244:245] op_sel:[0,1]
	v_pk_mul_f32 v[120:121], v[120:121], v[244:245] op_sel:[0,1]
	v_pk_fma_f32 v[118:119], v[154:155], v[118:119], v[158:159]
	v_pk_fma_f32 v[120:121], v[156:157], v[120:121], v[160:161]
	v_cvt_pk_bf16_f32 v232, v118, v119
	v_cvt_pk_bf16_f32 v233, v120, v121
	v_cndmask_b32_e64 v232, v232, v249, s[0:1]
	v_cndmask_b32_e64 v233, v233, v249, s[0:1]
	v_cndmask_b32_e32 v240, v122, v248, vcc
	v_cndmask_b32_e32 v241, v123, v248, vcc
	v_cndmask_b32_e32 v242, v124, v248, vcc
	v_cndmask_b32_e32 v243, v125, v248, vcc
	v_cvt_pk_bf16_f32 v218, v240, v241
	v_cvt_pk_bf16_f32 v219, v242, v243
	v_pk_mul_f32 v[122:123], v[122:123], v[244:245] op_sel:[0,1]
	v_pk_mul_f32 v[124:125], v[124:125], v[244:245] op_sel:[0,1]
	v_pk_fma_f32 v[122:123], v[150:151], v[122:123], v[146:147]
	v_pk_fma_f32 v[124:125], v[152:153], v[124:125], v[148:149]
	v_cvt_pk_bf16_f32 v234, v122, v123
	v_cvt_pk_bf16_f32 v235, v124, v125
	v_cndmask_b32_e64 v234, v234, v249, s[0:1]
	v_cndmask_b32_e64 v235, v235, v249, s[0:1]
	v_permlane16_swap_b32_e32 v216, v218
	v_permlane16_swap_b32_e32 v217, v219
	s_nop 1
	v_permlane16_swap_b32_e32 v232, v234
	v_permlane16_swap_b32_e32 v233, v235
	global_store_dwordx4 v246, v[216:219], s[56:57] sc1 nt
	global_store_dwordx4 v246, v[232:235], s[58:59] sc1
	v_cndmask_b32_e32 v240, v126, v248, vcc
	v_cndmask_b32_e32 v241, v127, v248, vcc
	v_cndmask_b32_e32 v242, v128, v248, vcc
	v_cndmask_b32_e32 v243, v129, v248, vcc
	v_cvt_pk_bf16_f32 v220, v240, v241
	v_cvt_pk_bf16_f32 v221, v242, v243
	v_pk_mul_f32 v[126:127], v[126:127], v[244:245] op_sel:[0,1]
	v_pk_mul_f32 v[128:129], v[128:129], v[244:245] op_sel:[0,1]
	v_pk_fma_f32 v[126:127], v[138:139], v[126:127], v[142:143]
	v_pk_fma_f32 v[128:129], v[140:141], v[128:129], v[144:145]
	v_cvt_pk_bf16_f32 v236, v126, v127
	v_cvt_pk_bf16_f32 v237, v128, v129
	v_cndmask_b32_e64 v236, v236, v249, s[0:1]
	v_cndmask_b32_e64 v237, v237, v249, s[0:1]
	v_cndmask_b32_e32 v240, v114, v248, vcc
	v_cndmask_b32_e32 v241, v115, v248, vcc
	v_cndmask_b32_e32 v242, v116, v248, vcc
	v_cndmask_b32_e32 v243, v117, v248, vcc
	v_cvt_pk_bf16_f32 v222, v240, v241
	v_cvt_pk_bf16_f32 v223, v242, v243
	v_pk_mul_f32 v[114:115], v[114:115], v[244:245] op_sel:[0,1]
	v_pk_mul_f32 v[116:117], v[116:117], v[244:245] op_sel:[0,1]
	v_pk_fma_f32 v[114:115], v[130:131], v[114:115], v[134:135]
	v_pk_fma_f32 v[116:117], v[132:133], v[116:117], v[136:137]
	v_cvt_pk_bf16_f32 v238, v114, v115
	v_cvt_pk_bf16_f32 v239, v116, v117
	v_cndmask_b32_e64 v238, v238, v249, s[0:1]
	v_cndmask_b32_e64 v239, v239, v249, s[0:1]
	v_permlane16_swap_b32_e32 v220, v222
	v_permlane16_swap_b32_e32 v221, v223
	s_nop 1
	v_permlane16_swap_b32_e32 v236, v238
	v_permlane16_swap_b32_e32 v237, v239
	global_store_dwordx4 v246, v[220:223], s[56:57] offset:256 sc1 nt
	global_store_dwordx4 v246, v[236:239], s[58:59] offset:256 sc1
	ds_read_b64 v[244:245], v183 offset:8320
	v_add_u32_e32 v247, 0x8000, v246
	s_waitcnt lgkmcnt(0)
	v_cndmask_b32_e32 v240, v110, v248, vcc
	v_cndmask_b32_e32 v241, v111, v248, vcc
	v_cndmask_b32_e32 v242, v112, v248, vcc
	v_cndmask_b32_e32 v243, v113, v248, vcc
	v_cvt_pk_bf16_f32 v216, v240, v241
	v_cvt_pk_bf16_f32 v217, v242, v243
	v_pk_mul_f32 v[110:111], v[110:111], v[244:245] op_sel:[0,1]
	v_pk_mul_f32 v[112:113], v[112:113], v[244:245] op_sel:[0,1]
	v_pk_fma_f32 v[110:111], v[154:155], v[110:111], v[158:159]
	v_pk_fma_f32 v[112:113], v[156:157], v[112:113], v[160:161]
	v_cvt_pk_bf16_f32 v232, v110, v111
	v_cvt_pk_bf16_f32 v233, v112, v113
	v_cndmask_b32_e64 v232, v232, v249, s[0:1]
	v_cndmask_b32_e64 v233, v233, v249, s[0:1]
	v_cndmask_b32_e32 v240, v106, v248, vcc
	v_cndmask_b32_e32 v241, v107, v248, vcc
	v_cndmask_b32_e32 v242, v108, v248, vcc
	v_cndmask_b32_e32 v243, v109, v248, vcc
	v_cvt_pk_bf16_f32 v218, v240, v241
	v_cvt_pk_bf16_f32 v219, v242, v243
	v_pk_mul_f32 v[106:107], v[106:107], v[244:245] op_sel:[0,1]
	v_pk_mul_f32 v[108:109], v[108:109], v[244:245] op_sel:[0,1]
	v_pk_fma_f32 v[106:107], v[150:151], v[106:107], v[146:147]
	v_pk_fma_f32 v[108:109], v[152:153], v[108:109], v[148:149]
	v_cvt_pk_bf16_f32 v234, v106, v107
	v_cvt_pk_bf16_f32 v235, v108, v109
	v_cndmask_b32_e64 v234, v234, v249, s[0:1]
	v_cndmask_b32_e64 v235, v235, v249, s[0:1]
	v_permlane16_swap_b32_e32 v216, v218
	v_permlane16_swap_b32_e32 v217, v219
	s_nop 1
	v_permlane16_swap_b32_e32 v232, v234
	v_permlane16_swap_b32_e32 v233, v235
	global_store_dwordx4 v247, v[216:219], s[56:57] sc1 nt
	global_store_dwordx4 v247, v[232:235], s[58:59] sc1
	v_cndmask_b32_e32 v240, v102, v248, vcc
	v_cndmask_b32_e32 v241, v103, v248, vcc
	v_cndmask_b32_e32 v242, v104, v248, vcc
	v_cndmask_b32_e32 v243, v105, v248, vcc
	v_cvt_pk_bf16_f32 v220, v240, v241
	v_cvt_pk_bf16_f32 v221, v242, v243
	v_pk_mul_f32 v[102:103], v[102:103], v[244:245] op_sel:[0,1]
	v_pk_mul_f32 v[104:105], v[104:105], v[244:245] op_sel:[0,1]
	v_pk_fma_f32 v[102:103], v[138:139], v[102:103], v[142:143]
	v_pk_fma_f32 v[104:105], v[140:141], v[104:105], v[144:145]
	v_cvt_pk_bf16_f32 v236, v102, v103
	v_cvt_pk_bf16_f32 v237, v104, v105
	v_cndmask_b32_e64 v236, v236, v249, s[0:1]
	v_cndmask_b32_e64 v237, v237, v249, s[0:1]
	v_cndmask_b32_e32 v240, v98, v248, vcc
	v_cndmask_b32_e32 v241, v99, v248, vcc
	v_cndmask_b32_e32 v242, v100, v248, vcc
	v_cndmask_b32_e32 v243, v101, v248, vcc
	v_cvt_pk_bf16_f32 v222, v240, v241
	v_cvt_pk_bf16_f32 v223, v242, v243
	v_pk_mul_f32 v[98:99], v[98:99], v[244:245] op_sel:[0,1]
	v_pk_mul_f32 v[100:101], v[100:101], v[244:245] op_sel:[0,1]
	v_pk_fma_f32 v[98:99], v[130:131], v[98:99], v[134:135]
	v_pk_fma_f32 v[100:101], v[132:133], v[100:101], v[136:137]
	v_cvt_pk_bf16_f32 v238, v98, v99
	v_cvt_pk_bf16_f32 v239, v100, v101
	v_cndmask_b32_e64 v238, v238, v249, s[0:1]
	v_cndmask_b32_e64 v239, v239, v249, s[0:1]
	v_permlane16_swap_b32_e32 v220, v222
	v_permlane16_swap_b32_e32 v221, v223
	s_nop 1
	v_permlane16_swap_b32_e32 v236, v238
	v_permlane16_swap_b32_e32 v237, v239
	global_store_dwordx4 v247, v[220:223], s[56:57] offset:256 sc1 nt
	global_store_dwordx4 v247, v[236:239], s[58:59] offset:256 sc1
	ds_read_b64 v[244:245], v183 offset:8448
	v_add_u32_e32 v247, 0x10000, v246
	s_waitcnt lgkmcnt(0)
	v_cndmask_b32_e32 v240, v94, v248, vcc
	v_cndmask_b32_e32 v241, v95, v248, vcc
	v_cndmask_b32_e32 v242, v96, v248, vcc
	v_cndmask_b32_e32 v243, v97, v248, vcc
	v_cvt_pk_bf16_f32 v216, v240, v241
	v_cvt_pk_bf16_f32 v217, v242, v243
	v_pk_mul_f32 v[94:95], v[94:95], v[244:245] op_sel:[0,1]
	v_pk_mul_f32 v[96:97], v[96:97], v[244:245] op_sel:[0,1]
	v_pk_fma_f32 v[94:95], v[154:155], v[94:95], v[158:159]
	v_pk_fma_f32 v[96:97], v[156:157], v[96:97], v[160:161]
	v_cvt_pk_bf16_f32 v232, v94, v95
	v_cvt_pk_bf16_f32 v233, v96, v97
	v_cndmask_b32_e64 v232, v232, v249, s[0:1]
	v_cndmask_b32_e64 v233, v233, v249, s[0:1]
	v_cndmask_b32_e32 v240, v90, v248, vcc
	v_cndmask_b32_e32 v241, v91, v248, vcc
	v_cndmask_b32_e32 v242, v92, v248, vcc
	v_cndmask_b32_e32 v243, v93, v248, vcc
	v_cvt_pk_bf16_f32 v218, v240, v241
	v_cvt_pk_bf16_f32 v219, v242, v243
	v_pk_mul_f32 v[90:91], v[90:91], v[244:245] op_sel:[0,1]
	v_pk_mul_f32 v[92:93], v[92:93], v[244:245] op_sel:[0,1]
	v_pk_fma_f32 v[90:91], v[150:151], v[90:91], v[146:147]
	v_pk_fma_f32 v[92:93], v[152:153], v[92:93], v[148:149]
	v_cvt_pk_bf16_f32 v234, v90, v91
	v_cvt_pk_bf16_f32 v235, v92, v93
	v_cndmask_b32_e64 v234, v234, v249, s[0:1]
	v_cndmask_b32_e64 v235, v235, v249, s[0:1]
	v_permlane16_swap_b32_e32 v216, v218
	v_permlane16_swap_b32_e32 v217, v219
	s_nop 1
	v_permlane16_swap_b32_e32 v232, v234
	v_permlane16_swap_b32_e32 v233, v235
	global_store_dwordx4 v247, v[216:219], s[56:57] sc1 nt
	global_store_dwordx4 v247, v[232:235], s[58:59] sc1
	v_cndmask_b32_e32 v240, v86, v248, vcc
	v_cndmask_b32_e32 v241, v87, v248, vcc
	v_cndmask_b32_e32 v242, v88, v248, vcc
	v_cndmask_b32_e32 v243, v89, v248, vcc
	v_cvt_pk_bf16_f32 v220, v240, v241
	v_cvt_pk_bf16_f32 v221, v242, v243
	v_pk_mul_f32 v[86:87], v[86:87], v[244:245] op_sel:[0,1]
	v_pk_mul_f32 v[88:89], v[88:89], v[244:245] op_sel:[0,1]
	v_pk_fma_f32 v[86:87], v[138:139], v[86:87], v[142:143]
	v_pk_fma_f32 v[88:89], v[140:141], v[88:89], v[144:145]
	v_cvt_pk_bf16_f32 v236, v86, v87
	v_cvt_pk_bf16_f32 v237, v88, v89
	v_cndmask_b32_e64 v236, v236, v249, s[0:1]
	v_cndmask_b32_e64 v237, v237, v249, s[0:1]
	v_cndmask_b32_e32 v240, v82, v248, vcc
	v_cndmask_b32_e32 v241, v83, v248, vcc
	v_cndmask_b32_e32 v242, v84, v248, vcc
	v_cndmask_b32_e32 v243, v85, v248, vcc
	v_cvt_pk_bf16_f32 v222, v240, v241
	v_cvt_pk_bf16_f32 v223, v242, v243
	v_pk_mul_f32 v[82:83], v[82:83], v[244:245] op_sel:[0,1]
	v_pk_mul_f32 v[84:85], v[84:85], v[244:245] op_sel:[0,1]
	v_pk_fma_f32 v[82:83], v[130:131], v[82:83], v[134:135]
	v_pk_fma_f32 v[84:85], v[132:133], v[84:85], v[136:137]
	v_cvt_pk_bf16_f32 v238, v82, v83
	v_cvt_pk_bf16_f32 v239, v84, v85
	v_cndmask_b32_e64 v238, v238, v249, s[0:1]
	v_cndmask_b32_e64 v239, v239, v249, s[0:1]
	v_permlane16_swap_b32_e32 v220, v222
	v_permlane16_swap_b32_e32 v221, v223
	s_nop 1
	v_permlane16_swap_b32_e32 v236, v238
	v_permlane16_swap_b32_e32 v237, v239
	global_store_dwordx4 v247, v[220:223], s[56:57] offset:256 sc1 nt
	global_store_dwordx4 v247, v[236:239], s[58:59] offset:256 sc1
	ds_read_b64 v[244:245], v183 offset:8576
	v_add_u32_e32 v247, 0x18000, v246
	s_waitcnt lgkmcnt(0)
	v_cndmask_b32_e32 v240, v78, v248, vcc
	v_cndmask_b32_e32 v241, v79, v248, vcc
	v_cndmask_b32_e32 v242, v80, v248, vcc
	v_cndmask_b32_e32 v243, v81, v248, vcc
	v_cvt_pk_bf16_f32 v216, v240, v241
	v_cvt_pk_bf16_f32 v217, v242, v243
	v_pk_mul_f32 v[78:79], v[78:79], v[244:245] op_sel:[0,1]
	v_pk_mul_f32 v[80:81], v[80:81], v[244:245] op_sel:[0,1]
	v_pk_fma_f32 v[78:79], v[154:155], v[78:79], v[158:159]
	v_pk_fma_f32 v[80:81], v[156:157], v[80:81], v[160:161]
	v_cvt_pk_bf16_f32 v232, v78, v79
	v_cvt_pk_bf16_f32 v233, v80, v81
	v_cndmask_b32_e64 v232, v232, v249, s[0:1]
	v_cndmask_b32_e64 v233, v233, v249, s[0:1]
	v_cndmask_b32_e32 v240, v74, v248, vcc
	v_cndmask_b32_e32 v241, v75, v248, vcc
	v_cndmask_b32_e32 v242, v76, v248, vcc
	v_cndmask_b32_e32 v243, v77, v248, vcc
	v_cvt_pk_bf16_f32 v218, v240, v241
	v_cvt_pk_bf16_f32 v219, v242, v243
	v_pk_mul_f32 v[74:75], v[74:75], v[244:245] op_sel:[0,1]
	v_pk_mul_f32 v[76:77], v[76:77], v[244:245] op_sel:[0,1]
	v_pk_fma_f32 v[74:75], v[150:151], v[74:75], v[146:147]
	v_pk_fma_f32 v[76:77], v[152:153], v[76:77], v[148:149]
	v_cvt_pk_bf16_f32 v234, v74, v75
	v_cvt_pk_bf16_f32 v235, v76, v77
	v_cndmask_b32_e64 v234, v234, v249, s[0:1]
	v_cndmask_b32_e64 v235, v235, v249, s[0:1]
	v_permlane16_swap_b32_e32 v216, v218
	v_permlane16_swap_b32_e32 v217, v219
	s_nop 1
	v_permlane16_swap_b32_e32 v232, v234
	v_permlane16_swap_b32_e32 v233, v235
	global_store_dwordx4 v247, v[216:219], s[56:57] sc1 nt
	global_store_dwordx4 v247, v[232:235], s[58:59] sc1
	v_cndmask_b32_e32 v240, v70, v248, vcc
	v_cndmask_b32_e32 v241, v71, v248, vcc
	v_cndmask_b32_e32 v242, v72, v248, vcc
	v_cndmask_b32_e32 v243, v73, v248, vcc
	v_cvt_pk_bf16_f32 v220, v240, v241
	v_cvt_pk_bf16_f32 v221, v242, v243
	v_pk_mul_f32 v[70:71], v[70:71], v[244:245] op_sel:[0,1]
	v_pk_mul_f32 v[72:73], v[72:73], v[244:245] op_sel:[0,1]
	v_pk_fma_f32 v[70:71], v[138:139], v[70:71], v[142:143]
	v_pk_fma_f32 v[72:73], v[140:141], v[72:73], v[144:145]
	v_cvt_pk_bf16_f32 v236, v70, v71
	v_cvt_pk_bf16_f32 v237, v72, v73
	v_cndmask_b32_e64 v236, v236, v249, s[0:1]
	v_cndmask_b32_e64 v237, v237, v249, s[0:1]
	v_cndmask_b32_e32 v240, v66, v248, vcc
	v_cndmask_b32_e32 v241, v67, v248, vcc
	v_cndmask_b32_e32 v242, v68, v248, vcc
	v_cndmask_b32_e32 v243, v69, v248, vcc
	v_cvt_pk_bf16_f32 v222, v240, v241
	v_cvt_pk_bf16_f32 v223, v242, v243
	v_pk_mul_f32 v[66:67], v[66:67], v[244:245] op_sel:[0,1]
	v_pk_mul_f32 v[68:69], v[68:69], v[244:245] op_sel:[0,1]
	v_pk_fma_f32 v[66:67], v[130:131], v[66:67], v[134:135]
	v_pk_fma_f32 v[68:69], v[132:133], v[68:69], v[136:137]
	v_cvt_pk_bf16_f32 v238, v66, v67
	v_cvt_pk_bf16_f32 v239, v68, v69
	v_cndmask_b32_e64 v238, v238, v249, s[0:1]
	v_cndmask_b32_e64 v239, v239, v249, s[0:1]
	v_permlane16_swap_b32_e32 v220, v222
	v_permlane16_swap_b32_e32 v221, v223
	s_nop 1
	v_permlane16_swap_b32_e32 v236, v238
	v_permlane16_swap_b32_e32 v237, v239
	global_store_dwordx4 v247, v[220:223], s[56:57] offset:256 sc1 nt
	global_store_dwordx4 v247, v[236:239], s[58:59] offset:256 sc1
	ds_read_b64 v[244:245], v183 offset:9216
	v_add_u32_e32 v247, 0x40000, v246
	s_waitcnt lgkmcnt(0)
	v_cndmask_b32_e32 v240, v62, v248, vcc
	v_cndmask_b32_e32 v241, v63, v248, vcc
	v_cndmask_b32_e32 v242, v64, v248, vcc
	v_cndmask_b32_e32 v243, v65, v248, vcc
	v_cvt_pk_bf16_f32 v216, v240, v241
	v_cvt_pk_bf16_f32 v217, v242, v243
	v_pk_mul_f32 v[62:63], v[62:63], v[244:245] op_sel:[0,1]
	v_pk_mul_f32 v[64:65], v[64:65], v[244:245] op_sel:[0,1]
	v_pk_fma_f32 v[62:63], v[154:155], v[62:63], v[158:159]
	v_pk_fma_f32 v[64:65], v[156:157], v[64:65], v[160:161]
	v_cvt_pk_bf16_f32 v232, v62, v63
	v_cvt_pk_bf16_f32 v233, v64, v65
	v_cndmask_b32_e64 v232, v232, v249, s[0:1]
	v_cndmask_b32_e64 v233, v233, v249, s[0:1]
	v_cndmask_b32_e32 v240, v58, v248, vcc
	v_cndmask_b32_e32 v241, v59, v248, vcc
	v_cndmask_b32_e32 v242, v60, v248, vcc
	v_cndmask_b32_e32 v243, v61, v248, vcc
	v_cvt_pk_bf16_f32 v218, v240, v241
	v_cvt_pk_bf16_f32 v219, v242, v243
	v_pk_mul_f32 v[58:59], v[58:59], v[244:245] op_sel:[0,1]
	v_pk_mul_f32 v[60:61], v[60:61], v[244:245] op_sel:[0,1]
	v_pk_fma_f32 v[58:59], v[150:151], v[58:59], v[146:147]
	v_pk_fma_f32 v[60:61], v[152:153], v[60:61], v[148:149]
	v_cvt_pk_bf16_f32 v234, v58, v59
	v_cvt_pk_bf16_f32 v235, v60, v61
	v_cndmask_b32_e64 v234, v234, v249, s[0:1]
	v_cndmask_b32_e64 v235, v235, v249, s[0:1]
	v_permlane16_swap_b32_e32 v216, v218
	v_permlane16_swap_b32_e32 v217, v219
	s_nop 1
	v_permlane16_swap_b32_e32 v232, v234
	v_permlane16_swap_b32_e32 v233, v235
	global_store_dwordx4 v247, v[216:219], s[56:57] sc1 nt
	global_store_dwordx4 v247, v[232:235], s[58:59] sc1
	v_cndmask_b32_e32 v240, v54, v248, vcc
	v_cndmask_b32_e32 v241, v55, v248, vcc
	v_cndmask_b32_e32 v242, v56, v248, vcc
	v_cndmask_b32_e32 v243, v57, v248, vcc
	v_cvt_pk_bf16_f32 v220, v240, v241
	v_cvt_pk_bf16_f32 v221, v242, v243
	v_pk_mul_f32 v[54:55], v[54:55], v[244:245] op_sel:[0,1]
	v_pk_mul_f32 v[56:57], v[56:57], v[244:245] op_sel:[0,1]
	v_pk_fma_f32 v[54:55], v[138:139], v[54:55], v[142:143]
	v_pk_fma_f32 v[56:57], v[140:141], v[56:57], v[144:145]
	v_cvt_pk_bf16_f32 v236, v54, v55
	v_cvt_pk_bf16_f32 v237, v56, v57
	v_cndmask_b32_e64 v236, v236, v249, s[0:1]
	v_cndmask_b32_e64 v237, v237, v249, s[0:1]
	v_cndmask_b32_e32 v240, v50, v248, vcc
	v_cndmask_b32_e32 v241, v51, v248, vcc
	v_cndmask_b32_e32 v242, v52, v248, vcc
	v_cndmask_b32_e32 v243, v53, v248, vcc
	v_cvt_pk_bf16_f32 v222, v240, v241
	v_cvt_pk_bf16_f32 v223, v242, v243
	v_pk_mul_f32 v[50:51], v[50:51], v[244:245] op_sel:[0,1]
	v_pk_mul_f32 v[52:53], v[52:53], v[244:245] op_sel:[0,1]
	v_pk_fma_f32 v[50:51], v[130:131], v[50:51], v[134:135]
	v_pk_fma_f32 v[52:53], v[132:133], v[52:53], v[136:137]
	v_cvt_pk_bf16_f32 v238, v50, v51
	v_cvt_pk_bf16_f32 v239, v52, v53
	v_cndmask_b32_e64 v238, v238, v249, s[0:1]
	v_cndmask_b32_e64 v239, v239, v249, s[0:1]
	v_permlane16_swap_b32_e32 v220, v222
	v_permlane16_swap_b32_e32 v221, v223
	s_nop 1
	v_permlane16_swap_b32_e32 v236, v238
	v_permlane16_swap_b32_e32 v237, v239
	global_store_dwordx4 v247, v[220:223], s[56:57] offset:256 sc1 nt
	global_store_dwordx4 v247, v[236:239], s[58:59] offset:256 sc1
	ds_read_b64 v[244:245], v183 offset:9344
	v_add_u32_e32 v247, 0x48000, v246
	s_waitcnt lgkmcnt(0)
	v_cndmask_b32_e32 v240, v46, v248, vcc
	v_cndmask_b32_e32 v241, v47, v248, vcc
	v_cndmask_b32_e32 v242, v48, v248, vcc
	v_cndmask_b32_e32 v243, v49, v248, vcc
	v_cvt_pk_bf16_f32 v216, v240, v241
	v_cvt_pk_bf16_f32 v217, v242, v243
	v_pk_mul_f32 v[46:47], v[46:47], v[244:245] op_sel:[0,1]
	v_pk_mul_f32 v[48:49], v[48:49], v[244:245] op_sel:[0,1]
	v_pk_fma_f32 v[46:47], v[154:155], v[46:47], v[158:159]
	v_pk_fma_f32 v[48:49], v[156:157], v[48:49], v[160:161]
	v_cvt_pk_bf16_f32 v232, v46, v47
	v_cvt_pk_bf16_f32 v233, v48, v49
	v_cndmask_b32_e64 v232, v232, v249, s[0:1]
	v_cndmask_b32_e64 v233, v233, v249, s[0:1]
	v_cndmask_b32_e32 v240, v42, v248, vcc
	v_cndmask_b32_e32 v241, v43, v248, vcc
	v_cndmask_b32_e32 v242, v44, v248, vcc
	v_cndmask_b32_e32 v243, v45, v248, vcc
	v_cvt_pk_bf16_f32 v218, v240, v241
	v_cvt_pk_bf16_f32 v219, v242, v243
	v_pk_mul_f32 v[42:43], v[42:43], v[244:245] op_sel:[0,1]
	v_pk_mul_f32 v[44:45], v[44:45], v[244:245] op_sel:[0,1]
	v_pk_fma_f32 v[42:43], v[150:151], v[42:43], v[146:147]
	v_pk_fma_f32 v[44:45], v[152:153], v[44:45], v[148:149]
	v_cvt_pk_bf16_f32 v234, v42, v43
	v_cvt_pk_bf16_f32 v235, v44, v45
	v_cndmask_b32_e64 v234, v234, v249, s[0:1]
	v_cndmask_b32_e64 v235, v235, v249, s[0:1]
	v_permlane16_swap_b32_e32 v216, v218
	v_permlane16_swap_b32_e32 v217, v219
	s_nop 1
	v_permlane16_swap_b32_e32 v232, v234
	v_permlane16_swap_b32_e32 v233, v235
	global_store_dwordx4 v247, v[216:219], s[56:57] sc1 nt
	global_store_dwordx4 v247, v[232:235], s[58:59] sc1
	v_cndmask_b32_e32 v240, v38, v248, vcc
	v_cndmask_b32_e32 v241, v39, v248, vcc
	v_cndmask_b32_e32 v242, v40, v248, vcc
	v_cndmask_b32_e32 v243, v41, v248, vcc
	v_cvt_pk_bf16_f32 v220, v240, v241
	v_cvt_pk_bf16_f32 v221, v242, v243
	v_pk_mul_f32 v[38:39], v[38:39], v[244:245] op_sel:[0,1]
	v_pk_mul_f32 v[40:41], v[40:41], v[244:245] op_sel:[0,1]
	v_pk_fma_f32 v[38:39], v[138:139], v[38:39], v[142:143]
	v_pk_fma_f32 v[40:41], v[140:141], v[40:41], v[144:145]
	v_cvt_pk_bf16_f32 v236, v38, v39
	v_cvt_pk_bf16_f32 v237, v40, v41
	v_cndmask_b32_e64 v236, v236, v249, s[0:1]
	v_cndmask_b32_e64 v237, v237, v249, s[0:1]
	v_cndmask_b32_e32 v240, v34, v248, vcc
	v_cndmask_b32_e32 v241, v35, v248, vcc
	v_cndmask_b32_e32 v242, v36, v248, vcc
	v_cndmask_b32_e32 v243, v37, v248, vcc
	v_cvt_pk_bf16_f32 v222, v240, v241
	v_cvt_pk_bf16_f32 v223, v242, v243
	v_pk_mul_f32 v[34:35], v[34:35], v[244:245] op_sel:[0,1]
	v_pk_mul_f32 v[36:37], v[36:37], v[244:245] op_sel:[0,1]
	v_pk_fma_f32 v[34:35], v[130:131], v[34:35], v[134:135]
	v_pk_fma_f32 v[36:37], v[132:133], v[36:37], v[136:137]
	v_cvt_pk_bf16_f32 v238, v34, v35
	v_cvt_pk_bf16_f32 v239, v36, v37
	v_cndmask_b32_e64 v238, v238, v249, s[0:1]
	v_cndmask_b32_e64 v239, v239, v249, s[0:1]
	v_permlane16_swap_b32_e32 v220, v222
	v_permlane16_swap_b32_e32 v221, v223
	s_nop 1
	v_permlane16_swap_b32_e32 v236, v238
	v_permlane16_swap_b32_e32 v237, v239
	global_store_dwordx4 v247, v[220:223], s[56:57] offset:256 sc1 nt
	global_store_dwordx4 v247, v[236:239], s[58:59] offset:256 sc1
	ds_read_b64 v[244:245], v183 offset:9472
	v_add_u32_e32 v247, 0x50000, v246
	s_waitcnt lgkmcnt(0)
	v_cndmask_b32_e32 v240, v30, v248, vcc
	v_cndmask_b32_e32 v241, v31, v248, vcc
	v_cndmask_b32_e32 v242, v32, v248, vcc
	v_cndmask_b32_e32 v243, v33, v248, vcc
	v_cvt_pk_bf16_f32 v216, v240, v241
	v_cvt_pk_bf16_f32 v217, v242, v243
	v_pk_mul_f32 v[30:31], v[30:31], v[244:245] op_sel:[0,1]
	v_pk_mul_f32 v[32:33], v[32:33], v[244:245] op_sel:[0,1]
	v_pk_fma_f32 v[30:31], v[154:155], v[30:31], v[158:159]
	v_pk_fma_f32 v[32:33], v[156:157], v[32:33], v[160:161]
	v_cvt_pk_bf16_f32 v232, v30, v31
	v_cvt_pk_bf16_f32 v233, v32, v33
	v_cndmask_b32_e64 v232, v232, v249, s[0:1]
	v_cndmask_b32_e64 v233, v233, v249, s[0:1]
	v_cndmask_b32_e32 v240, v26, v248, vcc
	v_cndmask_b32_e32 v241, v27, v248, vcc
	v_cndmask_b32_e32 v242, v28, v248, vcc
	v_cndmask_b32_e32 v243, v29, v248, vcc
	v_cvt_pk_bf16_f32 v218, v240, v241
	v_cvt_pk_bf16_f32 v219, v242, v243
	v_pk_mul_f32 v[26:27], v[26:27], v[244:245] op_sel:[0,1]
	v_pk_mul_f32 v[28:29], v[28:29], v[244:245] op_sel:[0,1]
	v_pk_fma_f32 v[26:27], v[150:151], v[26:27], v[146:147]
	v_pk_fma_f32 v[28:29], v[152:153], v[28:29], v[148:149]
	v_cvt_pk_bf16_f32 v234, v26, v27
	v_cvt_pk_bf16_f32 v235, v28, v29
	v_cndmask_b32_e64 v234, v234, v249, s[0:1]
	v_cndmask_b32_e64 v235, v235, v249, s[0:1]
	v_permlane16_swap_b32_e32 v216, v218
	v_permlane16_swap_b32_e32 v217, v219
	s_nop 1
	v_permlane16_swap_b32_e32 v232, v234
	v_permlane16_swap_b32_e32 v233, v235
	global_store_dwordx4 v247, v[216:219], s[56:57] sc1 nt
	global_store_dwordx4 v247, v[232:235], s[58:59] sc1
	v_cndmask_b32_e32 v240, v22, v248, vcc
	v_cndmask_b32_e32 v241, v23, v248, vcc
	v_cndmask_b32_e32 v242, v24, v248, vcc
	v_cndmask_b32_e32 v243, v25, v248, vcc
	v_cvt_pk_bf16_f32 v220, v240, v241
	v_cvt_pk_bf16_f32 v221, v242, v243
	v_pk_mul_f32 v[22:23], v[22:23], v[244:245] op_sel:[0,1]
	v_pk_mul_f32 v[24:25], v[24:25], v[244:245] op_sel:[0,1]
	v_pk_fma_f32 v[22:23], v[138:139], v[22:23], v[142:143]
	v_pk_fma_f32 v[24:25], v[140:141], v[24:25], v[144:145]
	v_cvt_pk_bf16_f32 v236, v22, v23
	v_cvt_pk_bf16_f32 v237, v24, v25
	v_cndmask_b32_e64 v236, v236, v249, s[0:1]
	v_cndmask_b32_e64 v237, v237, v249, s[0:1]
	v_cndmask_b32_e32 v240, v18, v248, vcc
	v_cndmask_b32_e32 v241, v19, v248, vcc
	v_cndmask_b32_e32 v242, v20, v248, vcc
	v_cndmask_b32_e32 v243, v21, v248, vcc
	v_cvt_pk_bf16_f32 v222, v240, v241
	v_cvt_pk_bf16_f32 v223, v242, v243
	v_pk_mul_f32 v[18:19], v[18:19], v[244:245] op_sel:[0,1]
	v_pk_mul_f32 v[20:21], v[20:21], v[244:245] op_sel:[0,1]
	v_pk_fma_f32 v[18:19], v[130:131], v[18:19], v[134:135]
	v_pk_fma_f32 v[20:21], v[132:133], v[20:21], v[136:137]
	v_cvt_pk_bf16_f32 v238, v18, v19
	v_cvt_pk_bf16_f32 v239, v20, v21
	v_cndmask_b32_e64 v238, v238, v249, s[0:1]
	v_cndmask_b32_e64 v239, v239, v249, s[0:1]
	v_permlane16_swap_b32_e32 v220, v222
	v_permlane16_swap_b32_e32 v221, v223
	s_nop 1
	v_permlane16_swap_b32_e32 v236, v238
	v_permlane16_swap_b32_e32 v237, v239
	global_store_dwordx4 v247, v[220:223], s[56:57] offset:256 sc1 nt
	global_store_dwordx4 v247, v[236:239], s[58:59] offset:256 sc1
	ds_read_b64 v[244:245], v183 offset:9600
	v_add_u32_e32 v247, 0x58000, v246
	s_waitcnt lgkmcnt(0)
	v_cndmask_b32_e32 v240, v14, v248, vcc
	v_cndmask_b32_e32 v241, v15, v248, vcc
	v_cndmask_b32_e32 v242, v16, v248, vcc
	v_cndmask_b32_e32 v243, v17, v248, vcc
	v_cvt_pk_bf16_f32 v216, v240, v241
	v_cvt_pk_bf16_f32 v217, v242, v243
	v_pk_mul_f32 v[14:15], v[14:15], v[244:245] op_sel:[0,1]
	v_pk_mul_f32 v[16:17], v[16:17], v[244:245] op_sel:[0,1]
	v_pk_fma_f32 v[14:15], v[154:155], v[14:15], v[158:159]
	v_pk_fma_f32 v[16:17], v[156:157], v[16:17], v[160:161]
	v_cvt_pk_bf16_f32 v232, v14, v15
	v_cvt_pk_bf16_f32 v233, v16, v17
	v_cndmask_b32_e64 v232, v232, v249, s[0:1]
	v_cndmask_b32_e64 v233, v233, v249, s[0:1]
	v_cndmask_b32_e32 v240, v10, v248, vcc
	v_cndmask_b32_e32 v241, v11, v248, vcc
	v_cndmask_b32_e32 v242, v12, v248, vcc
	v_cndmask_b32_e32 v243, v13, v248, vcc
	v_cvt_pk_bf16_f32 v218, v240, v241
	v_cvt_pk_bf16_f32 v219, v242, v243
	v_pk_mul_f32 v[10:11], v[10:11], v[244:245] op_sel:[0,1]
	v_pk_mul_f32 v[12:13], v[12:13], v[244:245] op_sel:[0,1]
	v_pk_fma_f32 v[10:11], v[150:151], v[10:11], v[146:147]
	v_pk_fma_f32 v[12:13], v[152:153], v[12:13], v[148:149]
	v_cvt_pk_bf16_f32 v234, v10, v11
	v_cvt_pk_bf16_f32 v235, v12, v13
	v_cndmask_b32_e64 v234, v234, v249, s[0:1]
	v_cndmask_b32_e64 v235, v235, v249, s[0:1]
	v_permlane16_swap_b32_e32 v216, v218
	v_permlane16_swap_b32_e32 v217, v219
	s_nop 1
	v_permlane16_swap_b32_e32 v232, v234
	v_permlane16_swap_b32_e32 v233, v235
	global_store_dwordx4 v247, v[216:219], s[56:57] sc1 nt
	global_store_dwordx4 v247, v[232:235], s[58:59] sc1
	v_cndmask_b32_e32 v240, v6, v248, vcc
	v_cndmask_b32_e32 v241, v7, v248, vcc
	v_cndmask_b32_e32 v242, v8, v248, vcc
	v_cndmask_b32_e32 v243, v9, v248, vcc
	v_cvt_pk_bf16_f32 v220, v240, v241
	v_cvt_pk_bf16_f32 v221, v242, v243
	v_pk_mul_f32 v[6:7], v[6:7], v[244:245] op_sel:[0,1]
	v_pk_mul_f32 v[8:9], v[8:9], v[244:245] op_sel:[0,1]
	v_pk_fma_f32 v[6:7], v[138:139], v[6:7], v[142:143]
	v_pk_fma_f32 v[8:9], v[140:141], v[8:9], v[144:145]
	v_cvt_pk_bf16_f32 v236, v6, v7
	v_cvt_pk_bf16_f32 v237, v8, v9
	v_cndmask_b32_e64 v236, v236, v249, s[0:1]
	v_cndmask_b32_e64 v237, v237, v249, s[0:1]
	v_cndmask_b32_e32 v240, v2, v248, vcc
	v_cndmask_b32_e32 v241, v3, v248, vcc
	v_cndmask_b32_e32 v242, v4, v248, vcc
	v_cndmask_b32_e32 v243, v5, v248, vcc
	v_cvt_pk_bf16_f32 v222, v240, v241
	v_cvt_pk_bf16_f32 v223, v242, v243
	v_pk_mul_f32 v[2:3], v[2:3], v[244:245] op_sel:[0,1]
	v_pk_mul_f32 v[4:5], v[4:5], v[244:245] op_sel:[0,1]
	v_pk_fma_f32 v[2:3], v[130:131], v[2:3], v[134:135]
	v_pk_fma_f32 v[4:5], v[132:133], v[4:5], v[136:137]
	v_cvt_pk_bf16_f32 v238, v2, v3
	v_cvt_pk_bf16_f32 v239, v4, v5
	v_cndmask_b32_e64 v238, v238, v249, s[0:1]
	v_cndmask_b32_e64 v239, v239, v249, s[0:1]
	v_permlane16_swap_b32_e32 v220, v222
	v_permlane16_swap_b32_e32 v221, v223
	s_nop 1
	v_permlane16_swap_b32_e32 v236, v238
	v_permlane16_swap_b32_e32 v237, v239
	global_store_dwordx4 v247, v[220:223], s[56:57] offset:256 sc1 nt
	global_store_dwordx4 v247, v[236:239], s[58:59] offset:256 sc1
